# FFN-in GEMMs: column-tile order rotated per XCD so XCDs do not stream the same weight tiles in lockstep
# speedup vs baseline: 1.0014x; 1.0014x over previous
; #define PG8_STAGE(bufoff, gbase, voff) do { if constexpr (!NOSTAGE) _Pragma("unroll") for (int _i = 0; _i < 2; ++_i) \
;         __builtin_amdgcn_global_load_lds((const unsigned*)((const char*)(gbase) + (size_t)_i * pstep##voff + v##voff), (PG8_LAS unsigned*)(lds + (bufoff) + ldsw + _i * 8192), 16, 0, 0); } while (0)
;     __host__ __device__ bool next(int i, Unit& u) const {
;         const long L = (long)i * G + c; if (L >= nwg) return false;
;         int wgid = (int)L; { const int q = nwg / NXCD, r = nwg % NXCD, xcd = wgid % NXCD, off = wgid / NXCD; wgid = (xcd < r ? xcd * (q + 1) : r * (q + 1) + (xcd - r) * q) + off; }
;         const int nig = WGM * nN, gid = wgid / nig, fm = gid * WGM, gsz = (nM - fm) < WGM ? (nM - fm) : WGM;
;         u.pm = fm + ((wgid % nig) % gsz); u.pn = (wgid % nig) / gsz; return true;
; template <class Epi, class Sched, bool ALIGN_EPI = true, bool SP2 = true, bool FULLLINE = false, bool NOSTAGE = false, bool FP8 = false>
; __device__ __forceinline__ void gemm_phase(PG8_LAS unsigned char* lds, const Gemm g, const Sched& S, const Epi& E) {
;     ...
;     const char* cA = PG8_ABASE(cur); const char* cB = PG8_BBASE(cur);
;     S.a_ready(cur);
;     if constexpr (SP2) {
;     PG8_STAGE(PG8_SB(0, 0), cB, offB); PG8_STAGE(PG8_SB(0, 1), cB + hstepB, offB); PG8_STAGE(PG8_SA(0, 0), cA, offA); PG8_STAGE(PG8_SA(0, 1), cA + hstepA, offA);
;     PG8_STAGE(PG8_SB(1, 0), cB + kstep, offB); PG8_STAGE(PG8_SA(1, 0), cA + kstep, offA); PG8_STAGE(PG8_SB(1, 1), cB + hstepB + kstep, offB);
.LBB0_755:
	s_add_u32 s96, s48, 0x41f00000
	s_addc_u32 s97, s49, 0
	s_cmp_lt_i32 s56, 8
	s_cselect_b64 s[6:7], -1, 0
	s_cmp_gt_i32 s57, 7
	s_cselect_b64 s[8:9], -1, 0
	s_and_b64 s[6:7], s[6:7], s[8:9]
	v_writelane_b32 v255, s96, 15
	s_andn2_b64 vcc, exec, s[6:7]
	s_nop 0
	v_writelane_b32 v255, s97, 16
	s_cbranch_vccnz .LBB0_846
	v_mov_b32_e32 v1, v0
	s_cmpk_gt_i32 s2, 0xaff
	v_readfirstlane_b32 s9, v0
	s_cbranch_scc1 .LBB0_774
	s_add_u32 s3, s48, 0x9700000
	s_addc_u32 s42, s49, 0
	s_ashr_i32 s44, s2, 31
	s_lshr_b32 s0, s44, 29
	s_add_i32 s0, s2, s0
	s_lshr_b32 s12, s9, 6
	s_ashr_i32 s1, s0, 3
	s_and_b32 s0, s0, -8
	s_lshr_b32 s13, s9, 8
	s_lshl_b32 s43, s12, 10
	s_sub_i32 s0, s2, s0
	s_cmp_lt_i32 s0, 0
	s_movk_i32 s6, 0x161
	s_cselect_b32 s6, s6, 0x160
	s_mul_i32 s0, s0, s6
	s_add_i32 s0, s0, s1
	s_mul_hi_i32 s1, s0, 0x2e8ba2e9
	s_lshr_b32 s6, s1, 31
	s_ashr_i32 s1, s1, 6
	s_add_i32 s1, s1, s6
	s_lshl_b32 s6, s1, 3
	s_mulk_i32 s1, 0x160
	s_sub_i32 s0, s0, s1
	s_sext_i32_i16 s1, s0
	s_bfe_u32 s1, s1, 0x3001c
	s_add_i32 s1, s0, s1
	s_sext_i32_i16 s7, s1
	s_and_b32 s1, s1, 0xfff8
	v_lshrrev_b32_e32 v1, 5, v0
	v_bfe_u32 v2, v0, 2, 2
	v_lshrrev_b32_e32 v4, 3, v0
	v_lshrrev_b32_e32 v3, 1, v0
	s_sub_i32 s0, s0, s1
	v_and_or_b32 v1, v1, 4, v2
	v_and_b32_e32 v2, 32, v4
	v_and_b32_e32 v3, 24, v3
	s_sext_i32_i16 s0, s0
	v_or3_b32 v3, v1, v2, v3
	v_lshlrev_b32_e32 v1, 4, v0
	v_and_b32_e32 v2, 32, v0
	s_lshr_b32 s8, s7, 3
	s_cmpk_lg_i32 s86, 0x100
	s_cbranch_scc1 .Lrot_skip_14390
	s_and_b32 s100, s2, 7
	s_mul_i32 s100, s100, 5
	s_add_i32 s8, s8, s100
	s_cmp_ge_i32 s8, 44
	s_cselect_b32 s100, 44, 0
	s_sub_i32 s8, s8, s100
.Lrot_skip_14390:
	s_add_i32 s74, s6, s0
	v_bitop3_b32 v1, v1, v2, 48 bitop3:0x6c
	v_and_b32_e32 v2, 64, v0
	s_ashr_i32 s75, s74, 31
	s_bfe_i64 s[10:11], s[8:9], 0x100000
	v_or_b32_e32 v5, v1, v2
	s_lshl_b64 s[6:7], s[74:75], 20
	s_lshl_b64 s[10:11], s[10:11], 20
	v_lshl_or_b32 v130, v3, 12, v5
	v_bfe_u32 v3, v0, 2, 4
	s_add_u32 s76, s3, s10
	v_and_or_b32 v4, v4, 48, v3
	s_addc_u32 s77, s42, s11
	v_mov_b32_e32 v131, 0
	s_add_i32 s45, s43, 0
	v_lshl_or_b32 v132, v4, 12, v5
	v_lshl_add_u64 v[4:5], s[76:77], 0, v[130:131]
	s_add_i32 m0, s45, 0x10000
	s_mov_b64 s[10:11], 0x40000
	global_load_lds_dwordx4 v130, s[76:77]
	v_lshl_add_u64 v[6:7], v[4:5], 0, s[10:11]
	s_add_i32 m0, s45, 0x12000
	s_mov_b64 s[14:15], 0x80000
	global_load_lds_dwordx4 v[6:7], off
	v_lshl_add_u64 v[6:7], v[4:5], 0, s[14:15]
	s_add_i32 m0, s45, 0x14000
	s_mov_b64 s[16:17], 0xc0000
	global_load_lds_dwordx4 v[6:7], off
	s_add_i32 m0, s45, 0x16000
	s_add_u32 s78, s58, s6
	v_lshl_add_u64 v[6:7], v[4:5], 0, s[16:17]
	s_addc_u32 s79, s59, s7
	v_mov_b32_e32 v133, v131
	global_load_lds_dwordx4 v[6:7], off
	v_lshl_add_u64 v[6:7], s[78:79], 0, v[132:133]
	s_mov_b32 m0, s45
	s_add_i32 s46, s45, 0x2000
	global_load_lds_dwordx4 v132, s[78:79]
	v_lshl_add_u64 v[8:9], v[6:7], 0, s[10:11]
	s_mov_b32 m0, s46
	s_add_i32 s47, s45, 0x4000
	global_load_lds_dwordx4 v[8:9], off
	v_lshl_add_u64 v[8:9], v[6:7], 0, s[14:15]
	s_mov_b32 m0, s47
	s_add_i32 s52, s45, 0x6000
	global_load_lds_dwordx4 v[8:9], off
	v_lshl_add_u64 v[8:9], v[6:7], 0, s[16:17]
	s_mov_b32 m0, s52
	s_mov_b64 s[6:7], 0x80
	global_load_lds_dwordx4 v[8:9], off
	v_lshl_add_u64 v[8:9], v[4:5], 0, s[6:7]
	s_add_i32 m0, s45, 0x18000
	s_mov_b64 s[10:11], 0x40080
	global_load_lds_dwordx4 v[8:9], off
	v_lshl_add_u64 v[8:9], v[4:5], 0, s[10:11]
	s_add_i32 m0, s45, 0x1a000
	s_add_i32 s53, s45, 0x8000
	global_load_lds_dwordx4 v[8:9], off
	v_lshl_add_u64 v[8:9], v[6:7], 0, s[6:7]
	s_mov_b32 m0, s53
	s_add_i32 s54, s45, 0xa000
	global_load_lds_dwordx4 v[8:9], off
	v_lshl_add_u64 v[6:7], v[6:7], 0, s[10:11]
	s_mov_b32 m0, s54
	s_mov_b64 s[6:7], 0x80080
	global_load_lds_dwordx4 v[6:7], off
	v_lshl_add_u64 v[6:7], v[4:5], 0, s[6:7]
	s_add_i32 m0, s45, 0x1c000
	s_mov_b64 s[6:7], 0xc0080
	global_load_lds_dwordx4 v[6:7], off
	v_lshl_add_u64 v[4:5], v[4:5], 0, s[6:7]
	s_add_i32 m0, s45, 0x1e000
	s_cmp_eq_u32 s13, 1
	global_load_lds_dwordx4 v[4:5], off
	s_cselect_b64 s[10:11], -1, 0
	s_cmp_lg_u32 s13, 1
	s_cbranch_scc1 .LBB0_759
	s_barrier

;     __host__ __device__ bool next(int i, Unit& u) const {
;         const long L = (long)i * G + c; if (L >= nwg) return false;
;         int wgid = (int)L; { const int q = nwg / NXCD, r = nwg % NXCD, xcd = wgid % NXCD, off = wgid / NXCD; wgid = (xcd < r ? xcd * (q + 1) : r * (q + 1) + (xcd - r) * q) + off; }
;         const int nig = WGM * nN, gid = wgid / nig, fm = gid * WGM, gsz = (nM - fm) < WGM ? (nM - fm) : WGM;
;         u.pm = fm + ((wgid % nig) % gsz); u.pn = (wgid % nig) / gsz; return true;
; template <class Epi, class Sched, bool ALIGN_EPI = true, bool SP2 = true, bool FULLLINE = false, bool NOSTAGE = false, bool FP8 = false>
; __device__ __forceinline__ void gemm_phase(PG8_LAS unsigned char* lds, const Gemm g, const Sched& S, const Epi& E) {
;     ...
;         const bool has_next = S.next(ui + 1, nxt);
;         const char* nA = has_next ? PG8_ABASE(nxt) : cA; const char* nB = has_next ? PG8_BBASE(nxt) : cB;
.LBB0_764:
	s_add_i32 s75, s75, 1
	s_mul_i32 s0, s75, s63
	s_mul_hi_u32 s1, s75, s86
	s_add_i32 s1, s1, s0
	s_mul_i32 s0, s75, s86
	s_add_u32 s70, s0, s2
	s_addc_u32 s71, s1, s44
	v_cmp_gt_i64_e32 vcc, s[70:71], v[138:139]
	v_cmp_lt_i64_e64 s[8:9], s[70:71], v[136:137]
	s_cbranch_vccnz .LBB0_766
	s_ashr_i32 s0, s70, 31
	s_lshr_b32 s0, s0, 29
	s_add_i32 s0, s70, s0
	s_ashr_i32 s1, s0, 3
	s_and_b32 s0, s0, -8
	s_sub_i32 s0, s70, s0
	s_cmp_lt_i32 s0, 0
	s_movk_i32 s33, 0x161
	s_cselect_b32 s33, s33, 0x160
	s_mul_i32 s0, s0, s33
	s_add_i32 s0, s0, s1
	s_mul_hi_i32 s1, s0, 0x2e8ba2e9
	s_lshr_b32 s33, s1, 31
	s_ashr_i32 s1, s1, 6
	s_add_i32 s1, s1, s33
	s_lshl_b32 s33, s1, 3
	s_sub_i32 s40, 64, s33
	s_min_i32 s40, s40, 8
	s_abs_i32 s41, s40
	v_cvt_f32_u32_e32 v2, s41
	s_sub_i32 s51, 0, s41
	s_mulk_i32 s1, 0x160
	s_sub_i32 s0, s0, s1
	v_rcp_iflag_f32_e32 v2, v2
	s_abs_i32 s1, s0
	s_xor_b32 s50, s0, s40
	s_ashr_i32 s50, s50, 31
	v_mul_f32_e32 v2, 0x4f7ffffe, v2
	v_cvt_u32_f32_e32 v2, v2
	s_nop 0
	v_readfirstlane_b32 s56, v2
	s_mul_i32 s51, s51, s56
	s_mul_hi_u32 s51, s56, s51
	s_add_i32 s56, s56, s51
	s_mul_hi_u32 s51, s1, s56
	s_mul_i32 s56, s51, s41
	s_sub_i32 s1, s1, s56
	s_add_i32 s57, s51, 1
	s_sub_i32 s56, s1, s41
	s_cmp_ge_u32 s1, s41
	s_cselect_b32 s51, s57, s51
	s_cselect_b32 s1, s56, s1
	s_add_i32 s56, s51, 1
	s_cmp_ge_u32 s1, s41
	s_cselect_b32 s1, s56, s51
	s_xor_b32 s1, s1, s50
	s_sub_i32 s66, s1, s50
	s_mul_i32 s1, s66, s40
	s_sub_i32 s0, s0, s1
	s_add_i32 s68, s33, s0
	s_cmpk_lg_i32 s86, 0x100
	s_cbranch_scc1 .Lrot_skip_14610
	s_and_b32 s100, s2, 7
	s_mul_i32 s100, s100, 5
	s_add_i32 s66, s66, s100
	s_cmp_ge_i32 s66, 44
	s_cselect_b32 s100, 44, 0
	s_sub_i32 s66, s66, s100
.Lrot_skip_14610:
.LBB0_766:
	s_ashr_i32 s69, s68, 31
	s_lshl_b64 s[40:41], s[68:69], 20
	s_add_u32 s70, s58, s40
	ds_read_b128 v[2:5], v1
	ds_read_b128 v[6:9], v1 offset:1024
	ds_read_b128 v[10:13], v1 offset:2048
	ds_read_b128 v[14:17], v1 offset:3072
	ds_read_b128 v[18:21], v142
	ds_read_b128 v[22:25], v142 offset:1024
	ds_read_b128 v[26:29], v142 offset:2048
	ds_read_b128 v[30:33], v142 offset:3072
	s_addc_u32 s71, s59, s41
	s_ashr_i32 s67, s66, 31
	s_lshl_b64 s[40:41], s[66:67], 20
	s_add_u32 s72, s3, s40
	s_addc_u32 s73, s42, s41
	s_and_b64 s[40:41], s[8:9], exec
	s_cselect_b32 s67, s71, s79
	s_cselect_b32 s69, s70, s78
	s_cselect_b32 s89, s73, s77
	s_cselect_b32 s90, s72, s76
	v_lshl_add_u64 v[140:141], s[78:79], 0, v[132:133]
	s_mov_b32 m0, s81
	v_lshl_add_u64 v[66:67], v[140:141], 0, s[12:13]
	ds_read_b128 v[34:37], v143
	ds_read_b128 v[38:41], v143 offset:1024
	ds_read_b128 v[42:45], v143 offset:2048
	ds_read_b128 v[46:49], v143 offset:3072
	ds_read_b128 v[50:53], v143 offset:4096
	ds_read_b128 v[54:57], v143 offset:5120
	ds_read_b128 v[58:61], v143 offset:6144
	ds_read_b128 v[62:65], v143 offset:7168
	global_load_lds_dwordx4 v[66:67], off
	v_lshl_add_u64 v[66:67], v[140:141], 0, s[14:15]
	s_mov_b32 m0, s82
	s_nop 0
	global_load_lds_dwordx4 v[66:67], off
	s_waitcnt vmcnt(16)
	s_waitcnt lgkmcnt(0)
	s_barrier
	s_waitcnt lgkmcnt(0)
	v_mfma_f32_16x16x32_bf16 v[86:89], v[10:13], v[50:53], 0
	v_mfma_f32_16x16x32_bf16 v[90:93], v[14:17], v[54:57], v[86:89]
	v_mfma_f32_16x16x32_bf16 v[86:89], v[2:5], v[58:61], 0
	v_mfma_f32_16x16x32_bf16 v[66:69], v[2:5], v[34:37], 0
	v_mfma_f32_16x16x32_bf16 v[70:73], v[10:13], v[34:37], 0
	v_mfma_f32_16x16x32_bf16 v[74:77], v[2:5], v[42:45], 0
	v_mfma_f32_16x16x32_bf16 v[78:81], v[10:13], v[42:45], 0
	v_mfma_f32_16x16x32_bf16 v[82:85], v[2:5], v[50:53], 0
	v_mfma_f32_16x16x32_bf16 v[94:97], v[6:9], v[62:65], v[86:89]
	v_mfma_f32_16x16x32_bf16 v[86:89], v[10:13], v[58:61], 0
	v_mfma_f32_16x16x32_bf16 v[66:69], v[6:9], v[38:41], v[66:69]
	v_mfma_f32_16x16x32_bf16 v[70:73], v[14:17], v[38:41], v[70:73]
	v_mfma_f32_16x16x32_bf16 v[74:77], v[6:9], v[46:49], v[74:77]
	v_mfma_f32_16x16x32_bf16 v[78:81], v[14:17], v[46:49], v[78:81]
	v_mfma_f32_16x16x32_bf16 v[82:85], v[6:9], v[54:57], v[82:85]
	v_mfma_f32_16x16x32_bf16 v[106:109], v[14:17], v[62:65], v[86:89]
	v_mfma_f32_16x16x32_bf16 v[86:89], v[18:21], v[34:37], 0
	v_mfma_f32_16x16x32_bf16 v[34:37], v[26:29], v[34:37], 0
	v_mfma_f32_16x16x32_bf16 v[110:113], v[22:25], v[38:41], v[86:89]
	v_mfma_f32_16x16x32_bf16 v[34:37], v[30:33], v[38:41], v[34:37]
	v_mfma_f32_16x16x32_bf16 v[38:41], v[18:21], v[42:45], 0
	v_mfma_f32_16x16x32_bf16 v[42:45], v[26:29], v[42:45], 0
	v_mfma_f32_16x16x32_bf16 v[38:41], v[22:25], v[46:49], v[38:41]
	v_mfma_f32_16x16x32_bf16 v[42:45], v[30:33], v[46:49], v[42:45]
	v_mfma_f32_16x16x32_bf16 v[46:49], v[18:21], v[50:53], 0
	v_mfma_f32_16x16x32_bf16 v[50:53], v[26:29], v[50:53], 0
	v_mfma_f32_16x16x32_bf16 v[46:49], v[22:25], v[54:57], v[46:49]
	v_mfma_f32_16x16x32_bf16 v[50:53], v[30:33], v[54:57], v[50:53]
	v_mfma_f32_16x16x32_bf16 v[54:57], v[18:21], v[58:61], 0
	v_mfma_f32_16x16x32_bf16 v[58:61], v[26:29], v[58:61], 0
	v_mfma_f32_16x16x32_bf16 v[54:57], v[22:25], v[62:65], v[54:57]
	v_mfma_f32_16x16x32_bf16 v[58:61], v[30:33], v[62:65], v[58:61]
	s_barrier
	v_lshl_add_u64 v[238:239], s[76:77], 0, v[130:131]
	s_mov_b32 m0, s83
	v_lshl_add_u64 v[146:147], v[238:239], 0, s[16:17]
	s_add_i32 s91, s83, 0x2000
	ds_read_b128 v[62:65], v143 offset:16384
	ds_read_b128 v[86:89], v143 offset:17408
	ds_read_b128 v[98:101], v143 offset:18432
	ds_read_b128 v[102:105], v143 offset:19456
	ds_read_b128 v[114:117], v143 offset:20480
	ds_read_b128 v[118:121], v143 offset:21504
	ds_read_b128 v[122:125], v143 offset:22528
	ds_read_b128 v[126:129], v143 offset:23552
	global_load_lds_dwordx4 v[146:147], off
	v_lshl_add_u64 v[146:147], v[238:239], 0, s[18:19]
	s_mov_b32 m0, s91
	s_add_i32 s92, s80, s43
	global_load_lds_dwordx4 v[146:147], off
	v_lshl_add_u64 v[146:147], v[238:239], 0, s[20:21]
	s_mov_b32 m0, s92
	s_add_i32 s40, s92, 0x2000
	global_load_lds_dwordx4 v[146:147], off
	v_lshl_add_u64 v[146:147], v[238:239], 0, s[22:23]
	s_mov_b32 m0, s40
	s_nop 0
	global_load_lds_dwordx4 v[146:147], off
	v_lshl_add_u64 v[146:147], v[140:141], 0, s[16:17]
	s_mov_b32 m0, s45
	s_nop 0
	global_load_lds_dwordx4 v[146:147], off
	v_lshl_add_u64 v[146:147], v[140:141], 0, s[18:19]
	s_mov_b32 m0, s46
	s_nop 0
	global_load_lds_dwordx4 v[146:147], off
	s_waitcnt vmcnt(16)
	s_waitcnt lgkmcnt(0)
	s_barrier
	s_waitcnt lgkmcnt(0)
	v_mfma_f32_16x16x32_bf16 v[146:149], v[2:5], v[62:65], 0
	v_mfma_f32_16x16x32_bf16 v[154:157], v[2:5], v[98:101], 0
	v_mfma_f32_16x16x32_bf16 v[162:165], v[2:5], v[114:117], 0
	v_mfma_f32_16x16x32_bf16 v[2:5], v[2:5], v[122:125], 0
	v_mfma_f32_16x16x32_bf16 v[146:149], v[6:9], v[86:89], v[146:149]
	v_mfma_f32_16x16x32_bf16 v[154:157], v[6:9], v[102:105], v[154:157]
	v_mfma_f32_16x16x32_bf16 v[162:165], v[6:9], v[118:121], v[162:165]
	v_mfma_f32_16x16x32_bf16 v[2:5], v[6:9], v[126:129], v[2:5]
	v_mfma_f32_16x16x32_bf16 v[6:9], v[10:13], v[122:125], 0
	v_mfma_f32_16x16x32_bf16 v[150:153], v[10:13], v[62:65], 0
	v_mfma_f32_16x16x32_bf16 v[158:161], v[10:13], v[98:101], 0
	v_mfma_f32_16x16x32_bf16 v[166:169], v[10:13], v[114:117], 0
	v_mfma_f32_16x16x32_bf16 v[10:13], v[14:17], v[126:129], v[6:9]
	v_mfma_f32_16x16x32_bf16 v[150:153], v[14:17], v[86:89], v[150:153]
	v_mfma_f32_16x16x32_bf16 v[158:161], v[14:17], v[102:105], v[158:161]
	v_mfma_f32_16x16x32_bf16 v[166:169], v[14:17], v[118:121], v[166:169]
	v_mfma_f32_16x16x32_bf16 v[6:9], v[18:21], v[62:65], 0
	v_mfma_f32_16x16x32_bf16 v[14:17], v[22:25], v[86:89], v[6:9]
	v_mfma_f32_16x16x32_bf16 v[6:9], v[26:29], v[62:65], 0
	v_mfma_f32_16x16x32_bf16 v[170:173], v[30:33], v[86:89], v[6:9]
	v_mfma_f32_16x16x32_bf16 v[6:9], v[18:21], v[98:101], 0
	v_mfma_f32_16x16x32_bf16 v[174:177], v[22:25], v[102:105], v[6:9]
	v_mfma_f32_16x16x32_bf16 v[6:9], v[26:29], v[98:101], 0
	v_mfma_f32_16x16x32_bf16 v[178:181], v[30:33], v[102:105], v[6:9]
	v_mfma_f32_16x16x32_bf16 v[6:9], v[18:21], v[114:117], 0
	v_mfma_f32_16x16x32_bf16 v[182:185], v[22:25], v[118:121], v[6:9]
	v_mfma_f32_16x16x32_bf16 v[6:9], v[26:29], v[114:117], 0
	v_mfma_f32_16x16x32_bf16 v[186:189], v[30:33], v[118:121], v[6:9]
	v_mfma_f32_16x16x32_bf16 v[6:9], v[18:21], v[122:125], 0
	v_mfma_f32_16x16x32_bf16 v[190:193], v[22:25], v[126:129], v[6:9]
	v_mfma_f32_16x16x32_bf16 v[6:9], v[26:29], v[122:125], 0
	v_mfma_f32_16x16x32_bf16 v[194:197], v[30:33], v[126:129], v[6:9]
	s_barrier
	s_nop 5
	ds_read_b128 v[6:9], v144
	ds_read_b128 v[26:29], v144 offset:1024
	ds_read_b128 v[30:33], v144 offset:2048
	ds_read_b128 v[62:65], v144 offset:3072
	ds_read_b128 v[198:201], v145
	ds_read_b128 v[202:205], v145 offset:1024
	ds_read_b128 v[206:209], v145 offset:2048
	ds_read_b128 v[210:213], v145 offset:3072
	s_mov_b32 m0, s47
	v_lshl_add_u64 v[86:87], v[140:141], 0, s[20:21]
	ds_read_b128 v[18:21], v143 offset:32768
	ds_read_b128 v[22:25], v143 offset:33792
	ds_read_b128 v[214:217], v143 offset:34816
	ds_read_b128 v[218:221], v143 offset:35840
	ds_read_b128 v[222:225], v143 offset:36864
	ds_read_b128 v[226:229], v143 offset:37888
	ds_read_b128 v[230:233], v143 offset:38912
	ds_read_b128 v[234:237], v143 offset:39936
	global_load_lds_dwordx4 v[86:87], off
	v_lshl_add_u64 v[86:87], v[140:141], 0, s[22:23]
	s_mov_b32 m0, s52
	s_nop 0
	global_load_lds_dwordx4 v[86:87], off
	s_waitcnt vmcnt(8)
	s_waitcnt lgkmcnt(0)
	s_barrier
; #define PG8_WAIT_V(n) asm volatile("s_waitcnt vmcnt(" #n ")" ::: "memory")
; template <class Epi, class Sched, bool ALIGN_EPI = true, bool SP2 = true, bool FULLLINE = false, bool NOSTAGE = false, bool FP8 = false>
; __device__ __forceinline__ void gemm_phase(PG8_LAS unsigned char* lds, const Gemm g, const Sched& S, const Epi& E) {
;     ...
;         static_assert(SP2, "only the SP2 loop is kept");
;         { const int t = 0; if constexpr (Epi::NST == 16) PG8_ITER(PG8_WAIT_V(24)); else if constexpr (Epi::NST == 8) PG8_ITER(PG8_WAIT_V(16)); else PG8_ITER(PG8_WAIT_V(8)); }
;         for (int t = 2; t < nt; t += 2) PG8_ITER(PG8_WAIT_V(8));
	s_waitcnt lgkmcnt(0)
	v_mfma_f32_16x16x32_bf16 v[66:69], v[6:9], v[18:21], v[66:69]
	v_mfma_f32_16x16x32_bf16 v[118:121], v[26:29], v[22:25], v[66:69]
	v_mfma_f32_16x16x32_bf16 v[66:69], v[30:33], v[18:21], v[70:73]
	v_mfma_f32_16x16x32_bf16 v[114:117], v[62:65], v[22:25], v[66:69]
	v_mfma_f32_16x16x32_bf16 v[66:69], v[6:9], v[214:217], v[74:77]
	v_mfma_f32_16x16x32_bf16 v[102:105], v[26:29], v[218:221], v[66:69]
	v_mfma_f32_16x16x32_bf16 v[66:69], v[30:33], v[214:217], v[78:81]
	v_mfma_f32_16x16x32_bf16 v[98:101], v[62:65], v[218:221], v[66:69]
	v_mfma_f32_16x16x32_bf16 v[66:69], v[6:9], v[222:225], v[82:85]
	v_mfma_f32_16x16x32_bf16 v[86:89], v[26:29], v[226:229], v[66:69]
	v_mfma_f32_16x16x32_bf16 v[66:69], v[30:33], v[222:225], v[90:93]
	v_mfma_f32_16x16x32_bf16 v[82:85], v[62:65], v[226:229], v[66:69]
	v_mfma_f32_16x16x32_bf16 v[66:69], v[6:9], v[230:233], v[94:97]
	v_mfma_f32_16x16x32_bf16 v[70:73], v[26:29], v[234:237], v[66:69]
	v_mfma_f32_16x16x32_bf16 v[66:69], v[30:33], v[230:233], v[106:109]
	v_mfma_f32_16x16x32_bf16 v[66:69], v[62:65], v[234:237], v[66:69]
	v_mfma_f32_16x16x32_bf16 v[74:77], v[198:201], v[18:21], v[110:113]
	v_mfma_f32_16x16x32_bf16 v[18:21], v[206:209], v[18:21], v[34:37]
	v_mfma_f32_16x16x32_bf16 v[122:125], v[210:213], v[22:25], v[18:21]
	v_mfma_f32_16x16x32_bf16 v[18:21], v[198:201], v[214:217], v[38:41]
	v_mfma_f32_16x16x32_bf16 v[110:113], v[202:205], v[218:221], v[18:21]
	v_mfma_f32_16x16x32_bf16 v[18:21], v[206:209], v[214:217], v[42:45]
	v_mfma_f32_16x16x32_bf16 v[106:109], v[210:213], v[218:221], v[18:21]
	v_mfma_f32_16x16x32_bf16 v[18:21], v[198:201], v[222:225], v[46:49]
	v_mfma_f32_16x16x32_bf16 v[94:97], v[202:205], v[226:229], v[18:21]
	v_mfma_f32_16x16x32_bf16 v[18:21], v[206:209], v[222:225], v[50:53]
	v_mfma_f32_16x16x32_bf16 v[90:93], v[210:213], v[226:229], v[18:21]
	v_mfma_f32_16x16x32_bf16 v[18:21], v[198:201], v[230:233], v[54:57]
	v_mfma_f32_16x16x32_bf16 v[78:81], v[202:205], v[234:237], v[18:21]
	v_mfma_f32_16x16x32_bf16 v[18:21], v[206:209], v[230:233], v[58:61]
	v_mfma_f32_16x16x32_bf16 v[126:129], v[202:205], v[22:25], v[74:77]
	v_mfma_f32_16x16x32_bf16 v[74:77], v[210:213], v[234:237], v[18:21]
	s_barrier
	s_add_i32 s41, s84, s43
	s_nop 3
	v_lshl_add_u64 v[18:19], v[238:239], 0, s[24:25]
	s_mov_b32 m0, s41
	s_add_i32 s50, s41, 0x2000
	ds_read_b128 v[42:45], v143 offset:49152
	ds_read_b128 v[46:49], v143 offset:50176
	ds_read_b128 v[214:217], v143 offset:51200
	ds_read_b128 v[218:221], v143 offset:52224
	ds_read_b128 v[222:225], v143 offset:53248
	ds_read_b128 v[226:229], v143 offset:54272
	ds_read_b128 v[230:233], v143 offset:55296
	ds_read_b128 v[234:237], v143 offset:56320
	global_load_lds_dwordx4 v[18:19], off
	v_lshl_add_u64 v[18:19], v[238:239], 0, s[26:27]
	s_mov_b32 m0, s50
	s_mov_b64 s[56:57], 0x80180
	s_add_i32 s51, s85, s43
	global_load_lds_dwordx4 v[18:19], off
	v_lshl_add_u64 v[18:19], v[238:239], 0, s[56:57]
	s_mov_b32 m0, s51
	s_mov_b64 s[56:57], 0xc0180
	s_add_i32 s33, s51, 0x2000
	global_load_lds_dwordx4 v[18:19], off
	v_lshl_add_u64 v[18:19], v[238:239], 0, s[56:57]
	s_mov_b32 m0, s33
	s_nop 0
	global_load_lds_dwordx4 v[18:19], off
	v_lshl_add_u64 v[18:19], v[140:141], 0, s[24:25]
	s_mov_b32 m0, s53
	s_nop 0
	global_load_lds_dwordx4 v[18:19], off
	v_lshl_add_u64 v[18:19], v[140:141], 0, s[26:27]
	s_mov_b32 m0, s54
	s_nop 0
	global_load_lds_dwordx4 v[18:19], off
	s_waitcnt vmcnt(8)
	s_waitcnt lgkmcnt(0)
	s_barrier
	s_waitcnt lgkmcnt(0)
	v_mfma_f32_16x16x32_bf16 v[18:21], v[6:9], v[42:45], v[146:149]
	v_mfma_f32_16x16x32_bf16 v[54:57], v[26:29], v[46:49], v[18:21]
	v_mfma_f32_16x16x32_bf16 v[18:21], v[30:33], v[42:45], v[150:153]
	v_mfma_f32_16x16x32_bf16 v[50:53], v[62:65], v[46:49], v[18:21]
	v_mfma_f32_16x16x32_bf16 v[18:21], v[6:9], v[214:217], v[154:157]
	v_mfma_f32_16x16x32_bf16 v[38:41], v[26:29], v[218:221], v[18:21]
	v_mfma_f32_16x16x32_bf16 v[18:21], v[30:33], v[214:217], v[158:161]
	v_mfma_f32_16x16x32_bf16 v[34:37], v[62:65], v[218:221], v[18:21]
	v_mfma_f32_16x16x32_bf16 v[18:21], v[6:9], v[222:225], v[162:165]
	v_mfma_f32_16x16x32_bf16 v[2:5], v[6:9], v[230:233], v[2:5]
	v_mfma_f32_16x16x32_bf16 v[22:25], v[26:29], v[226:229], v[18:21]
	v_mfma_f32_16x16x32_bf16 v[18:21], v[30:33], v[222:225], v[166:169]
	v_mfma_f32_16x16x32_bf16 v[6:9], v[26:29], v[234:237], v[2:5]
	v_mfma_f32_16x16x32_bf16 v[2:5], v[30:33], v[230:233], v[10:13]
	v_mfma_f32_16x16x32_bf16 v[18:21], v[62:65], v[226:229], v[18:21]
	v_mfma_f32_16x16x32_bf16 v[2:5], v[62:65], v[234:237], v[2:5]
	v_mfma_f32_16x16x32_bf16 v[10:13], v[198:201], v[42:45], v[14:17]
	v_mfma_f32_16x16x32_bf16 v[62:65], v[202:205], v[46:49], v[10:13]
	v_mfma_f32_16x16x32_bf16 v[10:13], v[206:209], v[42:45], v[170:173]
	v_mfma_f32_16x16x32_bf16 v[58:61], v[210:213], v[46:49], v[10:13]
	v_mfma_f32_16x16x32_bf16 v[10:13], v[198:201], v[214:217], v[174:177]
	v_mfma_f32_16x16x32_bf16 v[46:49], v[202:205], v[218:221], v[10:13]
	v_mfma_f32_16x16x32_bf16 v[10:13], v[206:209], v[214:217], v[178:181]
	v_mfma_f32_16x16x32_bf16 v[42:45], v[210:213], v[218:221], v[10:13]
	v_mfma_f32_16x16x32_bf16 v[10:13], v[198:201], v[222:225], v[182:185]
	v_mfma_f32_16x16x32_bf16 v[30:33], v[202:205], v[226:229], v[10:13]
	v_mfma_f32_16x16x32_bf16 v[10:13], v[206:209], v[222:225], v[186:189]
	v_mfma_f32_16x16x32_bf16 v[26:29], v[210:213], v[226:229], v[10:13]
	v_mfma_f32_16x16x32_bf16 v[10:13], v[198:201], v[230:233], v[190:193]
	v_mfma_f32_16x16x32_bf16 v[14:17], v[202:205], v[234:237], v[10:13]
	v_mfma_f32_16x16x32_bf16 v[10:13], v[206:209], v[230:233], v[194:197]
	v_mfma_f32_16x16x32_bf16 v[10:13], v[210:213], v[234:237], v[10:13]
	s_barrier
	s_add_u32 s78, s78, 0x80180
	s_addc_u32 s79, s79, 0
	s_add_u32 s56, s76, 0x200
	s_addc_u32 s57, s77, 0
	s_mov_b32 s76, 0

; #define PG8_STAGE(bufoff, gbase, voff) do { if constexpr (!NOSTAGE) _Pragma("unroll") for (int _i = 0; _i < 2; ++_i) \
;         __builtin_amdgcn_global_load_lds((const unsigned*)((const char*)(gbase) + (size_t)_i * pstep##voff + v##voff), (PG8_LAS unsigned*)(lds + (bufoff) + ldsw + _i * 8192), 16, 0, 0); } while (0)
; #define PG8_BAR __builtin_amdgcn_s_barrier()
;     __host__ __device__ bool next(int i, Unit& u) const {
;         const long L = (long)i * G + c; if (L >= nwg) return false;
;         int wgid = (int)L; { const int q = nwg / NXCD, r = nwg % NXCD, xcd = wgid % NXCD, off = wgid / NXCD; wgid = (xcd < r ? xcd * (q + 1) : r * (q + 1) + (xcd - r) * q) + off; }
;         const int nig = WGM * nN, gid = wgid / nig, fm = gid * WGM, gsz = (nM - fm) < WGM ? (nM - fm) : WGM;
;         u.pm = fm + ((wgid % nig) % gsz); u.pn = (wgid % nig) / gsz; return true;
; template <class Epi, class Sched, bool ALIGN_EPI = true, bool SP2 = true, bool FULLLINE = false, bool NOSTAGE = false, bool FP8 = false>
; __device__ __forceinline__ void gemm_phase(PG8_LAS unsigned char* lds, const Gemm g, const Sched& S, const Epi& E) {
;     ...
;     const char* cA = PG8_ABASE(cur); const char* cB = PG8_BBASE(cur);
;     S.a_ready(cur);
;     if constexpr (SP2) {
;     PG8_STAGE(PG8_SB(0, 0), cB, offB); PG8_STAGE(PG8_SB(0, 1), cB + hstepB, offB); PG8_STAGE(PG8_SA(0, 0), cA, offA); PG8_STAGE(PG8_SA(0, 1), cA + hstepA, offA);
;     PG8_STAGE(PG8_SB(1, 0), cB + kstep, offB); PG8_STAGE(PG8_SA(1, 0), cA + kstep, offA); PG8_STAGE(PG8_SB(1, 1), cB + hstepB + kstep, offB);
;     if (wr == 1) PG8_BAR;
.LBB0_1369:
	s_cmp_lt_i32 s56, 15
	s_cselect_b64 s[0:1], -1, 0
	s_cmp_gt_i32 s57, 14
	s_cselect_b64 s[6:7], -1, 0
	s_and_b64 s[0:1], s[0:1], s[6:7]
	s_andn2_b64 vcc, exec, s[0:1]
	s_cbranch_vccnz .LBB0_1460
	v_mov_b32_e32 v1, v0
	s_cmpk_gt_i32 s2, 0xaff
	v_readfirstlane_b32 s9, v0
	s_cbranch_scc1 .LBB0_1388
	s_add_u32 s3, s48, 0xc300000
	s_addc_u32 s42, s49, 0
	s_ashr_i32 s44, s2, 31
	s_lshr_b32 s0, s44, 29
	s_add_i32 s0, s2, s0
	s_lshr_b32 s12, s9, 6
	s_ashr_i32 s1, s0, 3
	s_and_b32 s0, s0, -8
	s_lshr_b32 s13, s9, 8
	s_lshl_b32 s43, s12, 10
	s_sub_i32 s0, s2, s0
	s_cmp_lt_i32 s0, 0
	s_movk_i32 s6, 0x161
	s_cselect_b32 s6, s6, 0x160
	s_mul_i32 s0, s0, s6
	s_add_i32 s0, s0, s1
	s_mul_hi_i32 s1, s0, 0x2e8ba2e9
	s_lshr_b32 s6, s1, 31
	s_ashr_i32 s1, s1, 6
	s_add_i32 s1, s1, s6
	s_lshl_b32 s6, s1, 3
	s_mulk_i32 s1, 0x160
	s_sub_i32 s0, s0, s1
	s_sext_i32_i16 s1, s0
	s_bfe_u32 s1, s1, 0x3001c
	s_add_i32 s1, s0, s1
	s_sext_i32_i16 s7, s1
	s_and_b32 s1, s1, 0xfff8
	v_lshrrev_b32_e32 v1, 5, v0
	v_bfe_u32 v2, v0, 2, 2
	v_lshrrev_b32_e32 v4, 3, v0
	v_lshrrev_b32_e32 v3, 1, v0
	s_sub_i32 s0, s0, s1
	v_and_or_b32 v1, v1, 4, v2
	v_and_b32_e32 v2, 32, v4
	v_and_b32_e32 v3, 24, v3
	s_sext_i32_i16 s0, s0
	v_or3_b32 v3, v1, v2, v3
	v_lshlrev_b32_e32 v1, 4, v0
	v_and_b32_e32 v2, 32, v0
	s_lshr_b32 s8, s7, 3
	s_cmpk_lg_i32 s86, 0x100
	s_cbranch_scc1 .Lrot_skip_27117
	s_and_b32 s100, s2, 7
	s_mul_i32 s100, s100, 5
	s_add_i32 s8, s8, s100
	s_cmp_ge_i32 s8, 44
	s_cselect_b32 s100, 44, 0
	s_sub_i32 s8, s8, s100
.Lrot_skip_27117:
	s_add_i32 s74, s6, s0
	v_bitop3_b32 v1, v1, v2, 48 bitop3:0x6c
	v_and_b32_e32 v2, 64, v0
	s_ashr_i32 s75, s74, 31
	s_bfe_i64 s[6:7], s[8:9], 0x100000
	v_or_b32_e32 v5, v1, v2
	s_lshl_b64 s[0:1], s[74:75], 20
	s_lshl_b64 s[6:7], s[6:7], 20
	v_lshl_or_b32 v130, v3, 12, v5
	v_bfe_u32 v3, v0, 2, 4
	s_add_u32 s76, s3, s6
	v_and_or_b32 v4, v4, 48, v3
	s_addc_u32 s77, s42, s7
	v_mov_b32_e32 v131, 0
	s_add_i32 s45, s43, 0
	v_lshl_or_b32 v132, v4, 12, v5
	v_lshl_add_u64 v[4:5], s[76:77], 0, v[130:131]
	s_add_i32 m0, s45, 0x10000
	s_mov_b64 s[6:7], 0x40000
	global_load_lds_dwordx4 v130, s[76:77]
	v_lshl_add_u64 v[6:7], v[4:5], 0, s[6:7]
	s_add_i32 m0, s45, 0x12000
	s_mov_b64 s[10:11], 0x80000
	global_load_lds_dwordx4 v[6:7], off
	v_lshl_add_u64 v[6:7], v[4:5], 0, s[10:11]
	s_add_i32 m0, s45, 0x14000
	s_mov_b64 s[14:15], 0xc0000
	global_load_lds_dwordx4 v[6:7], off
	s_add_i32 m0, s45, 0x16000
	s_add_u32 s78, s58, s0
	v_lshl_add_u64 v[6:7], v[4:5], 0, s[14:15]
	s_addc_u32 s79, s59, s1
	v_mov_b32_e32 v133, v131
	global_load_lds_dwordx4 v[6:7], off
	v_lshl_add_u64 v[6:7], s[78:79], 0, v[132:133]
	s_mov_b32 m0, s45
	s_add_i32 s46, s45, 0x2000
	global_load_lds_dwordx4 v132, s[78:79]
	v_lshl_add_u64 v[8:9], v[6:7], 0, s[6:7]
	s_mov_b32 m0, s46
	s_add_i32 s47, s45, 0x4000
	global_load_lds_dwordx4 v[8:9], off
	v_lshl_add_u64 v[8:9], v[6:7], 0, s[10:11]
	s_mov_b32 m0, s47
	s_add_i32 s52, s45, 0x6000
	global_load_lds_dwordx4 v[8:9], off
	v_lshl_add_u64 v[8:9], v[6:7], 0, s[14:15]
	s_mov_b32 m0, s52
	s_mov_b64 s[0:1], 0x80
	global_load_lds_dwordx4 v[8:9], off
	v_lshl_add_u64 v[8:9], v[4:5], 0, s[0:1]
	s_add_i32 m0, s45, 0x18000
	s_mov_b64 s[6:7], 0x40080
	global_load_lds_dwordx4 v[8:9], off
	v_lshl_add_u64 v[8:9], v[4:5], 0, s[6:7]
	s_add_i32 m0, s45, 0x1a000
	s_add_i32 s53, s45, 0x8000
	global_load_lds_dwordx4 v[8:9], off
	v_lshl_add_u64 v[8:9], v[6:7], 0, s[0:1]
	s_mov_b32 m0, s53
	s_add_i32 s54, s45, 0xa000
	global_load_lds_dwordx4 v[8:9], off
	v_lshl_add_u64 v[6:7], v[6:7], 0, s[6:7]
	s_mov_b32 m0, s54
	s_mov_b64 s[0:1], 0x80080
	global_load_lds_dwordx4 v[6:7], off
	v_lshl_add_u64 v[6:7], v[4:5], 0, s[0:1]
	s_add_i32 m0, s45, 0x1c000
	s_mov_b64 s[0:1], 0xc0080
	global_load_lds_dwordx4 v[6:7], off
	v_lshl_add_u64 v[4:5], v[4:5], 0, s[0:1]
	s_add_i32 m0, s45, 0x1e000
	s_cmp_eq_u32 s13, 1
	global_load_lds_dwordx4 v[4:5], off
	s_cselect_b64 s[10:11], -1, 0
	s_cmp_lg_u32 s13, 1
	s_cbranch_scc1 .LBB0_1373
	s_barrier

; template <class Epi, class Sched, bool ALIGN_EPI = true, bool SP2 = true, bool FULLLINE = false, bool NOSTAGE = false, bool FP8 = false>
; __device__ __forceinline__ void gemm_phase(PG8_LAS unsigned char* lds, const Gemm g, const Sched& S, const Epi& E) {
;     ...
;         const bool has_next = S.next(ui + 1, nxt);
;         const char* nA = has_next ? PG8_ABASE(nxt) : cA; const char* nB = has_next ? PG8_BBASE(nxt) : cB;
.Lrot_skip_27337:
.LBB0_1380:
	s_ashr_i32 s69, s68, 31
	s_lshl_b64 s[0:1], s[68:69], 20
	s_add_u32 s70, s58, s0
	ds_read_b128 v[2:5], v1
	ds_read_b128 v[6:9], v1 offset:1024
	ds_read_b128 v[10:13], v1 offset:2048
	ds_read_b128 v[14:17], v1 offset:3072
	ds_read_b128 v[18:21], v142
	ds_read_b128 v[22:25], v142 offset:1024
	ds_read_b128 v[26:29], v142 offset:2048
	ds_read_b128 v[30:33], v142 offset:3072
	s_addc_u32 s71, s59, s1
	s_ashr_i32 s67, s66, 31
	s_lshl_b64 s[0:1], s[66:67], 20
	s_add_u32 s72, s3, s0
	s_addc_u32 s73, s42, s1
	s_and_b64 s[0:1], s[8:9], exec
	s_cselect_b32 s67, s71, s79
	s_cselect_b32 s69, s70, s78
	s_cselect_b32 s89, s73, s77
	s_cselect_b32 s90, s72, s76
	v_lshl_add_u64 v[140:141], s[78:79], 0, v[132:133]
	s_mov_b32 m0, s81
	v_lshl_add_u64 v[66:67], v[140:141], 0, s[12:13]
	ds_read_b128 v[34:37], v143
	ds_read_b128 v[38:41], v143 offset:1024
	ds_read_b128 v[42:45], v143 offset:2048
	ds_read_b128 v[46:49], v143 offset:3072
	ds_read_b128 v[50:53], v143 offset:4096
	ds_read_b128 v[54:57], v143 offset:5120
	ds_read_b128 v[58:61], v143 offset:6144
	ds_read_b128 v[62:65], v143 offset:7168
	global_load_lds_dwordx4 v[66:67], off
	v_lshl_add_u64 v[66:67], v[140:141], 0, s[14:15]
	s_mov_b32 m0, s82
	s_nop 0
	global_load_lds_dwordx4 v[66:67], off
	s_waitcnt vmcnt(16)
	s_waitcnt lgkmcnt(0)
	s_barrier
	s_waitcnt lgkmcnt(0)
	v_mfma_f32_16x16x32_bf16 v[86:89], v[10:13], v[50:53], 0
	v_mfma_f32_16x16x32_bf16 v[90:93], v[14:17], v[54:57], v[86:89]
	v_mfma_f32_16x16x32_bf16 v[86:89], v[2:5], v[58:61], 0
	v_mfma_f32_16x16x32_bf16 v[66:69], v[2:5], v[34:37], 0
	v_mfma_f32_16x16x32_bf16 v[70:73], v[10:13], v[34:37], 0
	v_mfma_f32_16x16x32_bf16 v[74:77], v[2:5], v[42:45], 0
	v_mfma_f32_16x16x32_bf16 v[78:81], v[10:13], v[42:45], 0
	v_mfma_f32_16x16x32_bf16 v[82:85], v[2:5], v[50:53], 0
	v_mfma_f32_16x16x32_bf16 v[94:97], v[6:9], v[62:65], v[86:89]
	v_mfma_f32_16x16x32_bf16 v[86:89], v[10:13], v[58:61], 0
	v_mfma_f32_16x16x32_bf16 v[66:69], v[6:9], v[38:41], v[66:69]
	v_mfma_f32_16x16x32_bf16 v[70:73], v[14:17], v[38:41], v[70:73]
	v_mfma_f32_16x16x32_bf16 v[74:77], v[6:9], v[46:49], v[74:77]
	v_mfma_f32_16x16x32_bf16 v[78:81], v[14:17], v[46:49], v[78:81]
	v_mfma_f32_16x16x32_bf16 v[82:85], v[6:9], v[54:57], v[82:85]
	v_mfma_f32_16x16x32_bf16 v[106:109], v[14:17], v[62:65], v[86:89]
	v_mfma_f32_16x16x32_bf16 v[86:89], v[18:21], v[34:37], 0
	v_mfma_f32_16x16x32_bf16 v[34:37], v[26:29], v[34:37], 0
	v_mfma_f32_16x16x32_bf16 v[110:113], v[22:25], v[38:41], v[86:89]
	v_mfma_f32_16x16x32_bf16 v[34:37], v[30:33], v[38:41], v[34:37]
	v_mfma_f32_16x16x32_bf16 v[38:41], v[18:21], v[42:45], 0
	v_mfma_f32_16x16x32_bf16 v[42:45], v[26:29], v[42:45], 0
	v_mfma_f32_16x16x32_bf16 v[38:41], v[22:25], v[46:49], v[38:41]
	v_mfma_f32_16x16x32_bf16 v[42:45], v[30:33], v[46:49], v[42:45]
	v_mfma_f32_16x16x32_bf16 v[46:49], v[18:21], v[50:53], 0
	v_mfma_f32_16x16x32_bf16 v[50:53], v[26:29], v[50:53], 0
	v_mfma_f32_16x16x32_bf16 v[46:49], v[22:25], v[54:57], v[46:49]
	v_mfma_f32_16x16x32_bf16 v[50:53], v[30:33], v[54:57], v[50:53]
	v_mfma_f32_16x16x32_bf16 v[54:57], v[18:21], v[58:61], 0
	v_mfma_f32_16x16x32_bf16 v[58:61], v[26:29], v[58:61], 0
	v_mfma_f32_16x16x32_bf16 v[54:57], v[22:25], v[62:65], v[54:57]
	v_mfma_f32_16x16x32_bf16 v[58:61], v[30:33], v[62:65], v[58:61]
	s_barrier
	v_lshl_add_u64 v[238:239], s[76:77], 0, v[130:131]
	s_mov_b32 m0, s83
	v_lshl_add_u64 v[146:147], v[238:239], 0, s[16:17]
	s_add_i32 s91, s83, 0x2000
	ds_read_b128 v[62:65], v143 offset:16384
	ds_read_b128 v[86:89], v143 offset:17408
	ds_read_b128 v[98:101], v143 offset:18432
	ds_read_b128 v[102:105], v143 offset:19456
	ds_read_b128 v[114:117], v143 offset:20480
	ds_read_b128 v[118:121], v143 offset:21504
	ds_read_b128 v[122:125], v143 offset:22528
	ds_read_b128 v[126:129], v143 offset:23552
	global_load_lds_dwordx4 v[146:147], off
	v_lshl_add_u64 v[146:147], v[238:239], 0, s[18:19]
	s_mov_b32 m0, s91
	s_add_i32 s40, s80, s43
	global_load_lds_dwordx4 v[146:147], off
	v_lshl_add_u64 v[146:147], v[238:239], 0, s[20:21]
	s_mov_b32 m0, s40
	s_add_i32 s41, s40, 0x2000
	global_load_lds_dwordx4 v[146:147], off
	v_lshl_add_u64 v[146:147], v[238:239], 0, s[22:23]
	s_mov_b32 m0, s41
	s_nop 0
	global_load_lds_dwordx4 v[146:147], off
	v_lshl_add_u64 v[146:147], v[140:141], 0, s[16:17]
	s_mov_b32 m0, s45
	s_nop 0
	global_load_lds_dwordx4 v[146:147], off
	v_lshl_add_u64 v[146:147], v[140:141], 0, s[18:19]
	s_mov_b32 m0, s46
	s_nop 0
	global_load_lds_dwordx4 v[146:147], off
	s_waitcnt vmcnt(16)
	s_waitcnt lgkmcnt(0)
	s_barrier
	s_waitcnt lgkmcnt(0)
	v_mfma_f32_16x16x32_bf16 v[146:149], v[2:5], v[62:65], 0
	v_mfma_f32_16x16x32_bf16 v[154:157], v[2:5], v[98:101], 0
	v_mfma_f32_16x16x32_bf16 v[162:165], v[2:5], v[114:117], 0
	v_mfma_f32_16x16x32_bf16 v[2:5], v[2:5], v[122:125], 0
	v_mfma_f32_16x16x32_bf16 v[146:149], v[6:9], v[86:89], v[146:149]
	v_mfma_f32_16x16x32_bf16 v[154:157], v[6:9], v[102:105], v[154:157]
	v_mfma_f32_16x16x32_bf16 v[162:165], v[6:9], v[118:121], v[162:165]
	v_mfma_f32_16x16x32_bf16 v[2:5], v[6:9], v[126:129], v[2:5]
	v_mfma_f32_16x16x32_bf16 v[6:9], v[10:13], v[122:125], 0
	v_mfma_f32_16x16x32_bf16 v[150:153], v[10:13], v[62:65], 0
	v_mfma_f32_16x16x32_bf16 v[158:161], v[10:13], v[98:101], 0
	v_mfma_f32_16x16x32_bf16 v[166:169], v[10:13], v[114:117], 0
	v_mfma_f32_16x16x32_bf16 v[10:13], v[14:17], v[126:129], v[6:9]
	v_mfma_f32_16x16x32_bf16 v[150:153], v[14:17], v[86:89], v[150:153]
	v_mfma_f32_16x16x32_bf16 v[158:161], v[14:17], v[102:105], v[158:161]
	v_mfma_f32_16x16x32_bf16 v[166:169], v[14:17], v[118:121], v[166:169]
	v_mfma_f32_16x16x32_bf16 v[6:9], v[18:21], v[62:65], 0
	v_mfma_f32_16x16x32_bf16 v[14:17], v[22:25], v[86:89], v[6:9]
	v_mfma_f32_16x16x32_bf16 v[6:9], v[26:29], v[62:65], 0
	v_mfma_f32_16x16x32_bf16 v[170:173], v[30:33], v[86:89], v[6:9]
	v_mfma_f32_16x16x32_bf16 v[6:9], v[18:21], v[98:101], 0
	v_mfma_f32_16x16x32_bf16 v[174:177], v[22:25], v[102:105], v[6:9]
	v_mfma_f32_16x16x32_bf16 v[6:9], v[26:29], v[98:101], 0
	v_mfma_f32_16x16x32_bf16 v[178:181], v[30:33], v[102:105], v[6:9]
	v_mfma_f32_16x16x32_bf16 v[6:9], v[18:21], v[114:117], 0
	v_mfma_f32_16x16x32_bf16 v[182:185], v[22:25], v[118:121], v[6:9]
	v_mfma_f32_16x16x32_bf16 v[6:9], v[26:29], v[114:117], 0
	v_mfma_f32_16x16x32_bf16 v[186:189], v[30:33], v[118:121], v[6:9]
	v_mfma_f32_16x16x32_bf16 v[6:9], v[18:21], v[122:125], 0
	v_mfma_f32_16x16x32_bf16 v[190:193], v[22:25], v[126:129], v[6:9]
	v_mfma_f32_16x16x32_bf16 v[6:9], v[26:29], v[122:125], 0
	v_mfma_f32_16x16x32_bf16 v[194:197], v[30:33], v[126:129], v[6:9]
	s_barrier
	s_nop 5
	ds_read_b128 v[6:9], v144
	ds_read_b128 v[26:29], v144 offset:1024
	ds_read_b128 v[30:33], v144 offset:2048
	ds_read_b128 v[62:65], v144 offset:3072
	ds_read_b128 v[198:201], v145
	ds_read_b128 v[202:205], v145 offset:1024
	ds_read_b128 v[206:209], v145 offset:2048
	ds_read_b128 v[210:213], v145 offset:3072
	s_mov_b32 m0, s47
	v_lshl_add_u64 v[86:87], v[140:141], 0, s[20:21]
	ds_read_b128 v[18:21], v143 offset:32768
	ds_read_b128 v[22:25], v143 offset:33792
	ds_read_b128 v[214:217], v143 offset:34816
	ds_read_b128 v[218:221], v143 offset:35840
	ds_read_b128 v[222:225], v143 offset:36864
	ds_read_b128 v[226:229], v143 offset:37888
	ds_read_b128 v[230:233], v143 offset:38912
	ds_read_b128 v[234:237], v143 offset:39936
	global_load_lds_dwordx4 v[86:87], off
	v_lshl_add_u64 v[86:87], v[140:141], 0, s[22:23]
	s_mov_b32 m0, s52
	s_nop 0
	global_load_lds_dwordx4 v[86:87], off
	s_waitcnt vmcnt(8)
	s_waitcnt lgkmcnt(0)
	s_barrier
	s_waitcnt lgkmcnt(0)
	v_mfma_f32_16x16x32_bf16 v[66:69], v[6:9], v[18:21], v[66:69]
	v_mfma_f32_16x16x32_bf16 v[118:121], v[26:29], v[22:25], v[66:69]
	v_mfma_f32_16x16x32_bf16 v[66:69], v[30:33], v[18:21], v[70:73]
	v_mfma_f32_16x16x32_bf16 v[114:117], v[62:65], v[22:25], v[66:69]
	v_mfma_f32_16x16x32_bf16 v[66:69], v[6:9], v[214:217], v[74:77]
	v_mfma_f32_16x16x32_bf16 v[102:105], v[26:29], v[218:221], v[66:69]
	v_mfma_f32_16x16x32_bf16 v[66:69], v[30:33], v[214:217], v[78:81]
	v_mfma_f32_16x16x32_bf16 v[98:101], v[62:65], v[218:221], v[66:69]
	v_mfma_f32_16x16x32_bf16 v[66:69], v[6:9], v[222:225], v[82:85]
	v_mfma_f32_16x16x32_bf16 v[86:89], v[26:29], v[226:229], v[66:69]
	v_mfma_f32_16x16x32_bf16 v[66:69], v[30:33], v[222:225], v[90:93]
	v_mfma_f32_16x16x32_bf16 v[82:85], v[62:65], v[226:229], v[66:69]
	v_mfma_f32_16x16x32_bf16 v[66:69], v[6:9], v[230:233], v[94:97]
	v_mfma_f32_16x16x32_bf16 v[70:73], v[26:29], v[234:237], v[66:69]
	v_mfma_f32_16x16x32_bf16 v[66:69], v[30:33], v[230:233], v[106:109]
	v_mfma_f32_16x16x32_bf16 v[66:69], v[62:65], v[234:237], v[66:69]
	v_mfma_f32_16x16x32_bf16 v[74:77], v[198:201], v[18:21], v[110:113]
	v_mfma_f32_16x16x32_bf16 v[18:21], v[206:209], v[18:21], v[34:37]
	v_mfma_f32_16x16x32_bf16 v[122:125], v[210:213], v[22:25], v[18:21]
	v_mfma_f32_16x16x32_bf16 v[18:21], v[198:201], v[214:217], v[38:41]
	v_mfma_f32_16x16x32_bf16 v[110:113], v[202:205], v[218:221], v[18:21]
	v_mfma_f32_16x16x32_bf16 v[18:21], v[206:209], v[214:217], v[42:45]
	v_mfma_f32_16x16x32_bf16 v[106:109], v[210:213], v[218:221], v[18:21]
	v_mfma_f32_16x16x32_bf16 v[18:21], v[198:201], v[222:225], v[46:49]
	v_mfma_f32_16x16x32_bf16 v[94:97], v[202:205], v[226:229], v[18:21]
	v_mfma_f32_16x16x32_bf16 v[18:21], v[206:209], v[222:225], v[50:53]
	v_mfma_f32_16x16x32_bf16 v[90:93], v[210:213], v[226:229], v[18:21]
	v_mfma_f32_16x16x32_bf16 v[18:21], v[198:201], v[230:233], v[54:57]
	v_mfma_f32_16x16x32_bf16 v[78:81], v[202:205], v[234:237], v[18:21]
	v_mfma_f32_16x16x32_bf16 v[18:21], v[206:209], v[230:233], v[58:61]
	v_mfma_f32_16x16x32_bf16 v[126:129], v[202:205], v[22:25], v[74:77]
	v_mfma_f32_16x16x32_bf16 v[74:77], v[210:213], v[234:237], v[18:21]
	s_barrier
	s_add_i32 s50, s84, s43
	s_nop 3
	v_lshl_add_u64 v[18:19], v[238:239], 0, s[24:25]
	s_mov_b32 m0, s50
	s_add_i32 s51, s50, 0x2000
	ds_read_b128 v[42:45], v143 offset:49152
	ds_read_b128 v[46:49], v143 offset:50176
	ds_read_b128 v[214:217], v143 offset:51200
	ds_read_b128 v[218:221], v143 offset:52224
	ds_read_b128 v[222:225], v143 offset:53248
	ds_read_b128 v[226:229], v143 offset:54272
	ds_read_b128 v[230:233], v143 offset:55296
	ds_read_b128 v[234:237], v143 offset:56320
	global_load_lds_dwordx4 v[18:19], off
	v_lshl_add_u64 v[18:19], v[238:239], 0, s[26:27]
	s_mov_b32 m0, s51
	s_mov_b64 s[0:1], 0x80180
	s_add_i32 s33, s85, s43
	global_load_lds_dwordx4 v[18:19], off
	v_lshl_add_u64 v[18:19], v[238:239], 0, s[0:1]
	s_mov_b32 m0, s33
	s_mov_b64 s[0:1], 0xc0180
	s_add_i32 s56, s33, 0x2000
	global_load_lds_dwordx4 v[18:19], off
	v_lshl_add_u64 v[18:19], v[238:239], 0, s[0:1]
	s_mov_b32 m0, s56
	s_nop 0
	global_load_lds_dwordx4 v[18:19], off
	v_lshl_add_u64 v[18:19], v[140:141], 0, s[24:25]
	s_mov_b32 m0, s53
	s_nop 0
	global_load_lds_dwordx4 v[18:19], off
	v_lshl_add_u64 v[18:19], v[140:141], 0, s[26:27]
	s_mov_b32 m0, s54
	s_nop 0
	global_load_lds_dwordx4 v[18:19], off
	s_waitcnt vmcnt(8)
	s_waitcnt lgkmcnt(0)
	s_barrier
	s_waitcnt lgkmcnt(0)
	v_mfma_f32_16x16x32_bf16 v[18:21], v[6:9], v[42:45], v[146:149]
	v_mfma_f32_16x16x32_bf16 v[54:57], v[26:29], v[46:49], v[18:21]
	v_mfma_f32_16x16x32_bf16 v[18:21], v[30:33], v[42:45], v[150:153]
	v_mfma_f32_16x16x32_bf16 v[50:53], v[62:65], v[46:49], v[18:21]
	v_mfma_f32_16x16x32_bf16 v[18:21], v[6:9], v[214:217], v[154:157]
	v_mfma_f32_16x16x32_bf16 v[38:41], v[26:29], v[218:221], v[18:21]
	v_mfma_f32_16x16x32_bf16 v[18:21], v[30:33], v[214:217], v[158:161]
	v_mfma_f32_16x16x32_bf16 v[34:37], v[62:65], v[218:221], v[18:21]
	v_mfma_f32_16x16x32_bf16 v[18:21], v[6:9], v[222:225], v[162:165]
	v_mfma_f32_16x16x32_bf16 v[2:5], v[6:9], v[230:233], v[2:5]
	v_mfma_f32_16x16x32_bf16 v[22:25], v[26:29], v[226:229], v[18:21]
	v_mfma_f32_16x16x32_bf16 v[18:21], v[30:33], v[222:225], v[166:169]
	v_mfma_f32_16x16x32_bf16 v[6:9], v[26:29], v[234:237], v[2:5]
	v_mfma_f32_16x16x32_bf16 v[2:5], v[30:33], v[230:233], v[10:13]
	v_mfma_f32_16x16x32_bf16 v[18:21], v[62:65], v[226:229], v[18:21]
	v_mfma_f32_16x16x32_bf16 v[2:5], v[62:65], v[234:237], v[2:5]
	v_mfma_f32_16x16x32_bf16 v[10:13], v[198:201], v[42:45], v[14:17]
	v_mfma_f32_16x16x32_bf16 v[62:65], v[202:205], v[46:49], v[10:13]
	v_mfma_f32_16x16x32_bf16 v[10:13], v[206:209], v[42:45], v[170:173]
	v_mfma_f32_16x16x32_bf16 v[58:61], v[210:213], v[46:49], v[10:13]
	v_mfma_f32_16x16x32_bf16 v[10:13], v[198:201], v[214:217], v[174:177]
	v_mfma_f32_16x16x32_bf16 v[46:49], v[202:205], v[218:221], v[10:13]
	v_mfma_f32_16x16x32_bf16 v[10:13], v[206:209], v[214:217], v[178:181]
	v_mfma_f32_16x16x32_bf16 v[42:45], v[210:213], v[218:221], v[10:13]
	v_mfma_f32_16x16x32_bf16 v[10:13], v[198:201], v[222:225], v[182:185]
	v_mfma_f32_16x16x32_bf16 v[30:33], v[202:205], v[226:229], v[10:13]
	v_mfma_f32_16x16x32_bf16 v[10:13], v[206:209], v[222:225], v[186:189]
	v_mfma_f32_16x16x32_bf16 v[26:29], v[210:213], v[226:229], v[10:13]
	v_mfma_f32_16x16x32_bf16 v[10:13], v[198:201], v[230:233], v[190:193]
	v_mfma_f32_16x16x32_bf16 v[14:17], v[202:205], v[234:237], v[10:13]
	v_mfma_f32_16x16x32_bf16 v[10:13], v[206:209], v[230:233], v[194:197]
	v_mfma_f32_16x16x32_bf16 v[10:13], v[210:213], v[234:237], v[10:13]
	s_barrier
	s_add_u32 s78, s78, 0x80180
	s_addc_u32 s79, s79, 0
	s_add_u32 s57, s76, 0x200
	s_addc_u32 s76, s77, 0
	s_mov_b32 s77, 0

; #define PG8_STAGE(bufoff, gbase, voff) do { if constexpr (!NOSTAGE) _Pragma("unroll") for (int _i = 0; _i < 2; ++_i) \
;         __builtin_amdgcn_global_load_lds((const unsigned*)((const char*)(gbase) + (size_t)_i * pstep##voff + v##voff), (PG8_LAS unsigned*)(lds + (bufoff) + ldsw + _i * 8192), 16, 0, 0); } while (0)
; #define PG8_BAR __builtin_amdgcn_s_barrier()
;     __host__ __device__ bool next(int i, Unit& u) const {
;         const long L = (long)i * G + c; if (L >= nwg) return false;
;         int wgid = (int)L; { const int q = nwg / NXCD, r = nwg % NXCD, xcd = wgid % NXCD, off = wgid / NXCD; wgid = (xcd < r ? xcd * (q + 1) : r * (q + 1) + (xcd - r) * q) + off; }
;         const int nig = WGM * nN, gid = wgid / nig, fm = gid * WGM, gsz = (nM - fm) < WGM ? (nM - fm) : WGM;
;         u.pm = fm + ((wgid % nig) % gsz); u.pn = (wgid % nig) / gsz; return true;
; template <class Epi, class Sched, bool ALIGN_EPI = true, bool SP2 = true, bool FULLLINE = false, bool NOSTAGE = false, bool FP8 = false>
; __device__ __forceinline__ void gemm_phase(PG8_LAS unsigned char* lds, const Gemm g, const Sched& S, const Epi& E) {
;     ...
;     const char* cA = PG8_ABASE(cur); const char* cB = PG8_BBASE(cur);
;     S.a_ready(cur);
;     if constexpr (SP2) {
;     PG8_STAGE(PG8_SB(0, 0), cB, offB); PG8_STAGE(PG8_SB(0, 1), cB + hstepB, offB); PG8_STAGE(PG8_SA(0, 0), cA, offA); PG8_STAGE(PG8_SA(0, 1), cA + hstepA, offA);
;     PG8_STAGE(PG8_SB(1, 0), cB + kstep, offB); PG8_STAGE(PG8_SA(1, 0), cA + kstep, offA); PG8_STAGE(PG8_SB(1, 1), cB + hstepB + kstep, offB);
;     if (wr == 1) PG8_BAR;
.LBB0_2276:
	s_cmpk_gt_i32 s2, 0xaff
	v_readfirstlane_b32 s9, v0
	s_cbranch_scc1 .LBB0_2294
	s_add_u32 s3, s48, 0xef00000
	s_addc_u32 s42, s49, 0
	s_ashr_i32 s44, s2, 31
	s_lshr_b32 s0, s44, 29
	s_add_i32 s0, s2, s0
	s_lshr_b32 s12, s9, 6
	s_ashr_i32 s1, s0, 3
	s_and_b32 s0, s0, -8
	s_lshr_b32 s13, s9, 8
	s_lshl_b32 s43, s12, 10
	s_sub_i32 s0, s2, s0
	s_cmp_lt_i32 s0, 0
	s_movk_i32 s6, 0x161
	s_cselect_b32 s6, s6, 0x160
	s_mul_i32 s0, s0, s6
	s_add_i32 s0, s0, s1
	s_mul_hi_i32 s1, s0, 0x2e8ba2e9
	s_lshr_b32 s6, s1, 31
	s_ashr_i32 s1, s1, 6
	s_add_i32 s1, s1, s6
	s_lshl_b32 s6, s1, 3
	s_mulk_i32 s1, 0x160
	s_sub_i32 s0, s0, s1
	s_sext_i32_i16 s1, s0
	s_bfe_u32 s1, s1, 0x3001c
	s_add_i32 s1, s0, s1
	s_sext_i32_i16 s7, s1
	s_and_b32 s1, s1, 0xfff8
	v_lshrrev_b32_e32 v1, 5, v0
	v_bfe_u32 v2, v0, 2, 2
	v_lshrrev_b32_e32 v4, 3, v0
	v_lshrrev_b32_e32 v3, 1, v0
	s_sub_i32 s0, s0, s1
	v_and_or_b32 v1, v1, 4, v2
	v_and_b32_e32 v2, 32, v4
	v_and_b32_e32 v3, 24, v3
	s_sext_i32_i16 s0, s0
	v_or3_b32 v3, v1, v2, v3
	v_lshlrev_b32_e32 v1, 4, v0
	v_and_b32_e32 v2, 32, v0
	s_lshr_b32 s8, s7, 3
	s_cmpk_lg_i32 s86, 0x100
	s_cbranch_scc1 .Lrot_skip_46988
	s_and_b32 s100, s2, 7
	s_mul_i32 s100, s100, 5
	s_add_i32 s8, s8, s100
	s_cmp_ge_i32 s8, 44
	s_cselect_b32 s100, 44, 0
	s_sub_i32 s8, s8, s100
.Lrot_skip_46988:
	s_add_i32 s70, s6, s0
	v_bitop3_b32 v1, v1, v2, 48 bitop3:0x6c
	v_and_b32_e32 v2, 64, v0
	s_ashr_i32 s71, s70, 31
	s_bfe_i64 s[6:7], s[8:9], 0x100000
	v_or_b32_e32 v5, v1, v2
	s_lshl_b64 s[0:1], s[70:71], 20
	s_lshl_b64 s[6:7], s[6:7], 20
	v_lshl_or_b32 v130, v3, 12, v5
	v_bfe_u32 v3, v0, 2, 4
	s_add_u32 s72, s3, s6
	v_and_or_b32 v4, v4, 48, v3
	s_addc_u32 s73, s42, s7
	v_mov_b32_e32 v131, 0
	s_add_i32 s45, s43, 0
	v_lshl_or_b32 v132, v4, 12, v5
	v_lshl_add_u64 v[4:5], s[72:73], 0, v[130:131]
	s_add_i32 m0, s45, 0x10000
	s_mov_b64 s[6:7], 0x40000
	global_load_lds_dwordx4 v130, s[72:73]
	s_waitcnt lgkmcnt(0)
	v_lshl_add_u64 v[6:7], v[4:5], 0, s[6:7]
	s_add_i32 m0, s45, 0x12000
	s_mov_b64 s[10:11], 0x80000
	global_load_lds_dwordx4 v[6:7], off
	v_lshl_add_u64 v[6:7], v[4:5], 0, s[10:11]
	s_add_i32 m0, s45, 0x14000
	s_mov_b64 s[14:15], 0xc0000
	global_load_lds_dwordx4 v[6:7], off
	s_add_i32 m0, s45, 0x16000
	s_add_u32 s74, s58, s0
	v_lshl_add_u64 v[6:7], v[4:5], 0, s[14:15]
	s_addc_u32 s75, s59, s1
	v_mov_b32_e32 v133, v131
	global_load_lds_dwordx4 v[6:7], off
	v_lshl_add_u64 v[6:7], s[74:75], 0, v[132:133]
	s_mov_b32 m0, s45
	s_add_i32 s46, s45, 0x2000
	global_load_lds_dwordx4 v132, s[74:75]
	v_lshl_add_u64 v[8:9], v[6:7], 0, s[6:7]
	s_mov_b32 m0, s46
	s_add_i32 s47, s45, 0x4000
	global_load_lds_dwordx4 v[8:9], off
	v_lshl_add_u64 v[8:9], v[6:7], 0, s[10:11]
	s_mov_b32 m0, s47
	s_add_i32 s52, s45, 0x6000
	global_load_lds_dwordx4 v[8:9], off
	v_lshl_add_u64 v[8:9], v[6:7], 0, s[14:15]
	s_mov_b32 m0, s52
	s_mov_b64 s[0:1], 0x80
	global_load_lds_dwordx4 v[8:9], off
	v_lshl_add_u64 v[8:9], v[4:5], 0, s[0:1]
	s_add_i32 m0, s45, 0x18000
	s_mov_b64 s[6:7], 0x40080
	global_load_lds_dwordx4 v[8:9], off
	v_lshl_add_u64 v[8:9], v[4:5], 0, s[6:7]
	s_add_i32 m0, s45, 0x1a000
	s_add_i32 s53, s45, 0x8000
	global_load_lds_dwordx4 v[8:9], off
	v_lshl_add_u64 v[8:9], v[6:7], 0, s[0:1]
	s_mov_b32 m0, s53
	s_add_i32 s54, s45, 0xa000
	global_load_lds_dwordx4 v[8:9], off
	v_lshl_add_u64 v[6:7], v[6:7], 0, s[6:7]
	s_mov_b32 m0, s54
	s_mov_b64 s[0:1], 0x80080
	global_load_lds_dwordx4 v[6:7], off
	v_lshl_add_u64 v[6:7], v[4:5], 0, s[0:1]
	s_add_i32 m0, s45, 0x1c000
	s_mov_b64 s[0:1], 0xc0080
	global_load_lds_dwordx4 v[6:7], off
	v_lshl_add_u64 v[4:5], v[4:5], 0, s[0:1]
	s_add_i32 m0, s45, 0x1e000
	s_cmp_eq_u32 s13, 1
	global_load_lds_dwordx4 v[4:5], off
	s_cselect_b64 s[10:11], -1, 0
	s_cmp_lg_u32 s13, 1
	s_cbranch_scc1 .LBB0_2279
	s_barrier

;     __host__ __device__ bool next(int i, Unit& u) const {
;         const long L = (long)i * G + c; if (L >= nwg) return false;
;         int wgid = (int)L; { const int q = nwg / NXCD, r = nwg % NXCD, xcd = wgid % NXCD, off = wgid / NXCD; wgid = (xcd < r ? xcd * (q + 1) : r * (q + 1) + (xcd - r) * q) + off; }
;         const int nig = WGM * nN, gid = wgid / nig, fm = gid * WGM, gsz = (nM - fm) < WGM ? (nM - fm) : WGM;
;         u.pm = fm + ((wgid % nig) % gsz); u.pn = (wgid % nig) / gsz; return true;
; template <class Epi, class Sched, bool ALIGN_EPI = true, bool SP2 = true, bool FULLLINE = false, bool NOSTAGE = false, bool FP8 = false>
; __device__ __forceinline__ void gemm_phase(PG8_LAS unsigned char* lds, const Gemm g, const Sched& S, const Epi& E) {
;     ...
;         const bool has_next = S.next(ui + 1, nxt);
;         const char* nA = has_next ? PG8_ABASE(nxt) : cA; const char* nB = has_next ? PG8_BBASE(nxt) : cB;
.LBB0_2284:
	s_add_i32 s77, s77, 1
	s_mul_i32 s0, s77, s76
	s_mul_hi_u32 s1, s77, s86
	s_add_i32 s1, s1, s0
	s_mul_i32 s0, s77, s86
	s_add_u32 s66, s0, s2
	s_addc_u32 s67, s1, s44
	v_cmp_gt_i64_e32 vcc, s[66:67], v[138:139]
	v_cmp_lt_i64_e64 s[8:9], s[66:67], v[136:137]
	s_cbranch_vccnz .LBB0_2286
	s_ashr_i32 s0, s66, 31
	s_lshr_b32 s0, s0, 29
	s_add_i32 s0, s66, s0
	s_ashr_i32 s1, s0, 3
	s_and_b32 s0, s0, -8
	s_sub_i32 s0, s66, s0
	s_cmp_lt_i32 s0, 0
	s_movk_i32 s33, 0x161
	s_cselect_b32 s33, s33, 0x160
	s_mul_i32 s0, s0, s33
	s_add_i32 s0, s0, s1
	s_mul_hi_i32 s1, s0, 0x2e8ba2e9
	s_lshr_b32 s33, s1, 31
	s_ashr_i32 s1, s1, 6
	s_add_i32 s1, s1, s33
	s_lshl_b32 s33, s1, 3
	s_sub_i32 s40, 64, s33
	s_min_i32 s41, s40, 8
	s_abs_i32 s40, s41
	v_cvt_f32_u32_e32 v2, s40
	s_sub_i32 s51, 0, s40
	s_mulk_i32 s1, 0x160
	s_sub_i32 s0, s0, s1
	v_rcp_iflag_f32_e32 v2, v2
	s_abs_i32 s1, s0
	s_xor_b32 s50, s0, s41
	s_ashr_i32 s50, s50, 31
	v_mul_f32_e32 v2, 0x4f7ffffe, v2
	v_cvt_u32_f32_e32 v2, v2
	s_nop 0
	v_readfirstlane_b32 s56, v2
	s_mul_i32 s51, s51, s56
	s_mul_hi_u32 s51, s56, s51
	s_add_i32 s56, s56, s51
	s_mul_hi_u32 s51, s1, s56
	s_mul_i32 s56, s51, s40
	s_sub_i32 s1, s1, s56
	s_add_i32 s57, s51, 1
	s_sub_i32 s56, s1, s40
	s_cmp_ge_u32 s1, s40
	s_cselect_b32 s51, s57, s51
	s_cselect_b32 s1, s56, s1
	s_add_i32 s56, s51, 1
	s_cmp_ge_u32 s1, s40
	s_cselect_b32 s1, s56, s51
	s_xor_b32 s1, s1, s50
	s_sub_i32 s40, s1, s50
	s_mul_i32 s1, s40, s41
	s_sub_i32 s0, s0, s1
	s_add_i32 s62, s33, s0
	s_cmpk_lg_i32 s86, 0x100
	s_cbranch_scc1 .Lrot_skip_47208
	s_and_b32 s100, s2, 7
	s_mul_i32 s100, s100, 5
	s_add_i32 s40, s40, s100
	s_cmp_ge_i32 s40, 44
	s_cselect_b32 s100, 44, 0
	s_sub_i32 s40, s40, s100
.Lrot_skip_47208:
.LBB0_2286:
	s_ashr_i32 s63, s62, 31
	s_lshl_b64 s[0:1], s[62:63], 20
	s_add_u32 s66, s58, s0
	ds_read_b128 v[2:5], v1
	ds_read_b128 v[6:9], v1 offset:1024
	ds_read_b128 v[10:13], v1 offset:2048
	ds_read_b128 v[14:17], v1 offset:3072
	ds_read_b128 v[18:21], v142
	ds_read_b128 v[22:25], v142 offset:1024
	ds_read_b128 v[26:29], v142 offset:2048
	ds_read_b128 v[30:33], v142 offset:3072
	s_addc_u32 s67, s59, s1
	s_ashr_i32 s41, s40, 31
	s_lshl_b64 s[0:1], s[40:41], 20
	s_add_u32 s68, s3, s0
	s_addc_u32 s69, s42, s1
	s_and_b64 s[0:1], s[8:9], exec
	s_cselect_b32 s41, s67, s75
	s_cselect_b32 s63, s66, s74
	s_cselect_b32 s87, s69, s73
	s_cselect_b32 s88, s68, s72
	v_lshl_add_u64 v[140:141], s[74:75], 0, v[132:133]
	s_mov_b32 m0, s79
	v_lshl_add_u64 v[66:67], v[140:141], 0, s[12:13]
	ds_read_b128 v[34:37], v143
	ds_read_b128 v[38:41], v143 offset:1024
	ds_read_b128 v[42:45], v143 offset:2048
	ds_read_b128 v[46:49], v143 offset:3072
	ds_read_b128 v[50:53], v143 offset:4096
	ds_read_b128 v[54:57], v143 offset:5120
	ds_read_b128 v[58:61], v143 offset:6144
	ds_read_b128 v[62:65], v143 offset:7168
	global_load_lds_dwordx4 v[66:67], off
	v_lshl_add_u64 v[66:67], v[140:141], 0, s[14:15]
	s_mov_b32 m0, s80
	s_nop 0
	global_load_lds_dwordx4 v[66:67], off
	s_waitcnt vmcnt(16)
	s_waitcnt lgkmcnt(0)
	s_barrier
	s_waitcnt lgkmcnt(0)
	v_mfma_f32_16x16x32_bf16 v[86:89], v[10:13], v[50:53], 0
	v_mfma_f32_16x16x32_bf16 v[90:93], v[14:17], v[54:57], v[86:89]
	v_mfma_f32_16x16x32_bf16 v[86:89], v[2:5], v[58:61], 0
	v_mfma_f32_16x16x32_bf16 v[66:69], v[2:5], v[34:37], 0
	v_mfma_f32_16x16x32_bf16 v[70:73], v[10:13], v[34:37], 0
	v_mfma_f32_16x16x32_bf16 v[74:77], v[2:5], v[42:45], 0
	v_mfma_f32_16x16x32_bf16 v[78:81], v[10:13], v[42:45], 0
	v_mfma_f32_16x16x32_bf16 v[82:85], v[2:5], v[50:53], 0
	v_mfma_f32_16x16x32_bf16 v[94:97], v[6:9], v[62:65], v[86:89]
	v_mfma_f32_16x16x32_bf16 v[86:89], v[10:13], v[58:61], 0
	v_mfma_f32_16x16x32_bf16 v[66:69], v[6:9], v[38:41], v[66:69]
	v_mfma_f32_16x16x32_bf16 v[70:73], v[14:17], v[38:41], v[70:73]
	v_mfma_f32_16x16x32_bf16 v[74:77], v[6:9], v[46:49], v[74:77]
	v_mfma_f32_16x16x32_bf16 v[78:81], v[14:17], v[46:49], v[78:81]
	v_mfma_f32_16x16x32_bf16 v[82:85], v[6:9], v[54:57], v[82:85]
	v_mfma_f32_16x16x32_bf16 v[106:109], v[14:17], v[62:65], v[86:89]
	v_mfma_f32_16x16x32_bf16 v[86:89], v[18:21], v[34:37], 0
	v_mfma_f32_16x16x32_bf16 v[34:37], v[26:29], v[34:37], 0
	v_mfma_f32_16x16x32_bf16 v[110:113], v[22:25], v[38:41], v[86:89]
	v_mfma_f32_16x16x32_bf16 v[34:37], v[30:33], v[38:41], v[34:37]
	v_mfma_f32_16x16x32_bf16 v[38:41], v[18:21], v[42:45], 0
	v_mfma_f32_16x16x32_bf16 v[42:45], v[26:29], v[42:45], 0
	v_mfma_f32_16x16x32_bf16 v[38:41], v[22:25], v[46:49], v[38:41]
	v_mfma_f32_16x16x32_bf16 v[42:45], v[30:33], v[46:49], v[42:45]
	v_mfma_f32_16x16x32_bf16 v[46:49], v[18:21], v[50:53], 0
	v_mfma_f32_16x16x32_bf16 v[50:53], v[26:29], v[50:53], 0
	v_mfma_f32_16x16x32_bf16 v[46:49], v[22:25], v[54:57], v[46:49]
	v_mfma_f32_16x16x32_bf16 v[50:53], v[30:33], v[54:57], v[50:53]
	v_mfma_f32_16x16x32_bf16 v[54:57], v[18:21], v[58:61], 0
	v_mfma_f32_16x16x32_bf16 v[58:61], v[26:29], v[58:61], 0
	v_mfma_f32_16x16x32_bf16 v[54:57], v[22:25], v[62:65], v[54:57]
	v_mfma_f32_16x16x32_bf16 v[58:61], v[30:33], v[62:65], v[58:61]
	s_barrier
	v_lshl_add_u64 v[238:239], s[72:73], 0, v[130:131]
	s_mov_b32 m0, s81
	v_lshl_add_u64 v[146:147], v[238:239], 0, s[16:17]
	s_add_i32 s89, s81, 0x2000
	ds_read_b128 v[62:65], v143 offset:16384
	ds_read_b128 v[86:89], v143 offset:17408
	ds_read_b128 v[98:101], v143 offset:18432
	ds_read_b128 v[102:105], v143 offset:19456
	ds_read_b128 v[114:117], v143 offset:20480
	ds_read_b128 v[118:121], v143 offset:21504
	ds_read_b128 v[122:125], v143 offset:22528
	ds_read_b128 v[126:129], v143 offset:23552
	global_load_lds_dwordx4 v[146:147], off
	v_lshl_add_u64 v[146:147], v[238:239], 0, s[18:19]
	s_mov_b32 m0, s89
	s_add_i32 s90, s78, s43
	global_load_lds_dwordx4 v[146:147], off
	v_lshl_add_u64 v[146:147], v[238:239], 0, s[20:21]
	s_mov_b32 m0, s90
	s_add_i32 s91, s90, 0x2000
	global_load_lds_dwordx4 v[146:147], off
	v_lshl_add_u64 v[146:147], v[238:239], 0, s[22:23]
	s_mov_b32 m0, s91
	s_nop 0
	global_load_lds_dwordx4 v[146:147], off
	v_lshl_add_u64 v[146:147], v[140:141], 0, s[16:17]
	s_mov_b32 m0, s45
	s_nop 0
	global_load_lds_dwordx4 v[146:147], off
	v_lshl_add_u64 v[146:147], v[140:141], 0, s[18:19]
	s_mov_b32 m0, s46
	s_nop 0
	global_load_lds_dwordx4 v[146:147], off
	s_waitcnt vmcnt(16)
	s_waitcnt lgkmcnt(0)
	s_barrier
	s_waitcnt lgkmcnt(0)
	v_mfma_f32_16x16x32_bf16 v[146:149], v[2:5], v[62:65], 0
	v_mfma_f32_16x16x32_bf16 v[154:157], v[2:5], v[98:101], 0
	v_mfma_f32_16x16x32_bf16 v[162:165], v[2:5], v[114:117], 0
	v_mfma_f32_16x16x32_bf16 v[2:5], v[2:5], v[122:125], 0
	v_mfma_f32_16x16x32_bf16 v[146:149], v[6:9], v[86:89], v[146:149]
	v_mfma_f32_16x16x32_bf16 v[154:157], v[6:9], v[102:105], v[154:157]
	v_mfma_f32_16x16x32_bf16 v[162:165], v[6:9], v[118:121], v[162:165]
	v_mfma_f32_16x16x32_bf16 v[2:5], v[6:9], v[126:129], v[2:5]
	v_mfma_f32_16x16x32_bf16 v[6:9], v[10:13], v[122:125], 0
	v_mfma_f32_16x16x32_bf16 v[150:153], v[10:13], v[62:65], 0
	v_mfma_f32_16x16x32_bf16 v[158:161], v[10:13], v[98:101], 0
	v_mfma_f32_16x16x32_bf16 v[166:169], v[10:13], v[114:117], 0
	v_mfma_f32_16x16x32_bf16 v[10:13], v[14:17], v[126:129], v[6:9]
	v_mfma_f32_16x16x32_bf16 v[150:153], v[14:17], v[86:89], v[150:153]
	v_mfma_f32_16x16x32_bf16 v[158:161], v[14:17], v[102:105], v[158:161]
	v_mfma_f32_16x16x32_bf16 v[166:169], v[14:17], v[118:121], v[166:169]
	v_mfma_f32_16x16x32_bf16 v[6:9], v[18:21], v[62:65], 0
	v_mfma_f32_16x16x32_bf16 v[14:17], v[22:25], v[86:89], v[6:9]
	v_mfma_f32_16x16x32_bf16 v[6:9], v[26:29], v[62:65], 0
	v_mfma_f32_16x16x32_bf16 v[170:173], v[30:33], v[86:89], v[6:9]
	v_mfma_f32_16x16x32_bf16 v[6:9], v[18:21], v[98:101], 0
	v_mfma_f32_16x16x32_bf16 v[174:177], v[22:25], v[102:105], v[6:9]
	v_mfma_f32_16x16x32_bf16 v[6:9], v[26:29], v[98:101], 0
	v_mfma_f32_16x16x32_bf16 v[178:181], v[30:33], v[102:105], v[6:9]
	v_mfma_f32_16x16x32_bf16 v[6:9], v[18:21], v[114:117], 0
	v_mfma_f32_16x16x32_bf16 v[182:185], v[22:25], v[118:121], v[6:9]
	v_mfma_f32_16x16x32_bf16 v[6:9], v[26:29], v[114:117], 0
	v_mfma_f32_16x16x32_bf16 v[186:189], v[30:33], v[118:121], v[6:9]
	v_mfma_f32_16x16x32_bf16 v[6:9], v[18:21], v[122:125], 0
	v_mfma_f32_16x16x32_bf16 v[190:193], v[22:25], v[126:129], v[6:9]
	v_mfma_f32_16x16x32_bf16 v[6:9], v[26:29], v[122:125], 0
	v_mfma_f32_16x16x32_bf16 v[194:197], v[30:33], v[126:129], v[6:9]
	s_barrier
	s_nop 5
	ds_read_b128 v[6:9], v144
	ds_read_b128 v[26:29], v144 offset:1024
	ds_read_b128 v[30:33], v144 offset:2048
	ds_read_b128 v[62:65], v144 offset:3072
	ds_read_b128 v[198:201], v145
	ds_read_b128 v[202:205], v145 offset:1024
	ds_read_b128 v[206:209], v145 offset:2048
	ds_read_b128 v[210:213], v145 offset:3072
	s_mov_b32 m0, s47
	v_lshl_add_u64 v[86:87], v[140:141], 0, s[20:21]
	ds_read_b128 v[18:21], v143 offset:32768
	ds_read_b128 v[22:25], v143 offset:33792
	ds_read_b128 v[214:217], v143 offset:34816
	ds_read_b128 v[218:221], v143 offset:35840
	ds_read_b128 v[222:225], v143 offset:36864
	ds_read_b128 v[226:229], v143 offset:37888
	ds_read_b128 v[230:233], v143 offset:38912
	ds_read_b128 v[234:237], v143 offset:39936
	global_load_lds_dwordx4 v[86:87], off
	v_lshl_add_u64 v[86:87], v[140:141], 0, s[22:23]
	s_mov_b32 m0, s52
	s_nop 0
	global_load_lds_dwordx4 v[86:87], off
	s_waitcnt vmcnt(8)
	s_waitcnt lgkmcnt(0)
	s_barrier
	s_waitcnt lgkmcnt(0)
	v_mfma_f32_16x16x32_bf16 v[66:69], v[6:9], v[18:21], v[66:69]
	v_mfma_f32_16x16x32_bf16 v[118:121], v[26:29], v[22:25], v[66:69]
	v_mfma_f32_16x16x32_bf16 v[66:69], v[30:33], v[18:21], v[70:73]
	v_mfma_f32_16x16x32_bf16 v[114:117], v[62:65], v[22:25], v[66:69]
	v_mfma_f32_16x16x32_bf16 v[66:69], v[6:9], v[214:217], v[74:77]
	v_mfma_f32_16x16x32_bf16 v[102:105], v[26:29], v[218:221], v[66:69]
	v_mfma_f32_16x16x32_bf16 v[66:69], v[30:33], v[214:217], v[78:81]
	v_mfma_f32_16x16x32_bf16 v[98:101], v[62:65], v[218:221], v[66:69]
	v_mfma_f32_16x16x32_bf16 v[66:69], v[6:9], v[222:225], v[82:85]
	v_mfma_f32_16x16x32_bf16 v[86:89], v[26:29], v[226:229], v[66:69]
	v_mfma_f32_16x16x32_bf16 v[66:69], v[30:33], v[222:225], v[90:93]
	v_mfma_f32_16x16x32_bf16 v[82:85], v[62:65], v[226:229], v[66:69]
	v_mfma_f32_16x16x32_bf16 v[66:69], v[6:9], v[230:233], v[94:97]
	v_mfma_f32_16x16x32_bf16 v[70:73], v[26:29], v[234:237], v[66:69]
	v_mfma_f32_16x16x32_bf16 v[66:69], v[30:33], v[230:233], v[106:109]
	v_mfma_f32_16x16x32_bf16 v[66:69], v[62:65], v[234:237], v[66:69]
	v_mfma_f32_16x16x32_bf16 v[74:77], v[198:201], v[18:21], v[110:113]
	v_mfma_f32_16x16x32_bf16 v[18:21], v[206:209], v[18:21], v[34:37]
	v_mfma_f32_16x16x32_bf16 v[122:125], v[210:213], v[22:25], v[18:21]
	v_mfma_f32_16x16x32_bf16 v[18:21], v[198:201], v[214:217], v[38:41]
	v_mfma_f32_16x16x32_bf16 v[110:113], v[202:205], v[218:221], v[18:21]
	v_mfma_f32_16x16x32_bf16 v[18:21], v[206:209], v[214:217], v[42:45]
	v_mfma_f32_16x16x32_bf16 v[106:109], v[210:213], v[218:221], v[18:21]
	v_mfma_f32_16x16x32_bf16 v[18:21], v[198:201], v[222:225], v[46:49]
	v_mfma_f32_16x16x32_bf16 v[94:97], v[202:205], v[226:229], v[18:21]
	v_mfma_f32_16x16x32_bf16 v[18:21], v[206:209], v[222:225], v[50:53]
	v_mfma_f32_16x16x32_bf16 v[90:93], v[210:213], v[226:229], v[18:21]
	v_mfma_f32_16x16x32_bf16 v[18:21], v[198:201], v[230:233], v[54:57]
	v_mfma_f32_16x16x32_bf16 v[78:81], v[202:205], v[234:237], v[18:21]
	v_mfma_f32_16x16x32_bf16 v[18:21], v[206:209], v[230:233], v[58:61]
	v_mfma_f32_16x16x32_bf16 v[126:129], v[202:205], v[22:25], v[74:77]
	v_mfma_f32_16x16x32_bf16 v[74:77], v[210:213], v[234:237], v[18:21]
	s_barrier
	s_add_i32 s50, s82, s43
	s_nop 3
	v_lshl_add_u64 v[18:19], v[238:239], 0, s[24:25]
	s_mov_b32 m0, s50
	s_add_i32 s51, s50, 0x2000
	ds_read_b128 v[42:45], v143 offset:49152
	ds_read_b128 v[46:49], v143 offset:50176
	ds_read_b128 v[214:217], v143 offset:51200
	ds_read_b128 v[218:221], v143 offset:52224
	ds_read_b128 v[222:225], v143 offset:53248
	ds_read_b128 v[226:229], v143 offset:54272
	ds_read_b128 v[230:233], v143 offset:55296
	ds_read_b128 v[234:237], v143 offset:56320
	global_load_lds_dwordx4 v[18:19], off
	v_lshl_add_u64 v[18:19], v[238:239], 0, s[26:27]
	s_mov_b32 m0, s51
	s_mov_b64 s[0:1], 0x80180
	s_add_i32 s33, s83, s43
	global_load_lds_dwordx4 v[18:19], off
	v_lshl_add_u64 v[18:19], v[238:239], 0, s[0:1]
	s_mov_b32 m0, s33
	s_mov_b64 s[0:1], 0xc0180
	s_add_i32 s56, s33, 0x2000
	global_load_lds_dwordx4 v[18:19], off
	v_lshl_add_u64 v[18:19], v[238:239], 0, s[0:1]
	s_mov_b32 m0, s56
	s_nop 0
	global_load_lds_dwordx4 v[18:19], off
	v_lshl_add_u64 v[18:19], v[140:141], 0, s[24:25]
	s_mov_b32 m0, s53
	s_nop 0
	global_load_lds_dwordx4 v[18:19], off
	v_lshl_add_u64 v[18:19], v[140:141], 0, s[26:27]
	s_mov_b32 m0, s54
	s_nop 0
	global_load_lds_dwordx4 v[18:19], off
	s_waitcnt vmcnt(8)
	s_waitcnt lgkmcnt(0)
	s_barrier
	s_waitcnt lgkmcnt(0)
	v_mfma_f32_16x16x32_bf16 v[18:21], v[6:9], v[42:45], v[146:149]
	v_mfma_f32_16x16x32_bf16 v[54:57], v[26:29], v[46:49], v[18:21]
	v_mfma_f32_16x16x32_bf16 v[18:21], v[30:33], v[42:45], v[150:153]
	v_mfma_f32_16x16x32_bf16 v[50:53], v[62:65], v[46:49], v[18:21]
	v_mfma_f32_16x16x32_bf16 v[18:21], v[6:9], v[214:217], v[154:157]
	v_mfma_f32_16x16x32_bf16 v[38:41], v[26:29], v[218:221], v[18:21]
	v_mfma_f32_16x16x32_bf16 v[18:21], v[30:33], v[214:217], v[158:161]
	v_mfma_f32_16x16x32_bf16 v[34:37], v[62:65], v[218:221], v[18:21]
	v_mfma_f32_16x16x32_bf16 v[18:21], v[6:9], v[222:225], v[162:165]
	v_mfma_f32_16x16x32_bf16 v[2:5], v[6:9], v[230:233], v[2:5]
	v_mfma_f32_16x16x32_bf16 v[22:25], v[26:29], v[226:229], v[18:21]
	v_mfma_f32_16x16x32_bf16 v[18:21], v[30:33], v[222:225], v[166:169]
	v_mfma_f32_16x16x32_bf16 v[6:9], v[26:29], v[234:237], v[2:5]
	v_mfma_f32_16x16x32_bf16 v[2:5], v[30:33], v[230:233], v[10:13]
	v_mfma_f32_16x16x32_bf16 v[18:21], v[62:65], v[226:229], v[18:21]
	v_mfma_f32_16x16x32_bf16 v[2:5], v[62:65], v[234:237], v[2:5]
	v_mfma_f32_16x16x32_bf16 v[10:13], v[198:201], v[42:45], v[14:17]
	v_mfma_f32_16x16x32_bf16 v[62:65], v[202:205], v[46:49], v[10:13]
	v_mfma_f32_16x16x32_bf16 v[10:13], v[206:209], v[42:45], v[170:173]
	v_mfma_f32_16x16x32_bf16 v[58:61], v[210:213], v[46:49], v[10:13]
	v_mfma_f32_16x16x32_bf16 v[10:13], v[198:201], v[214:217], v[174:177]
	v_mfma_f32_16x16x32_bf16 v[46:49], v[202:205], v[218:221], v[10:13]
	v_mfma_f32_16x16x32_bf16 v[10:13], v[206:209], v[214:217], v[178:181]
	v_mfma_f32_16x16x32_bf16 v[42:45], v[210:213], v[218:221], v[10:13]
	v_mfma_f32_16x16x32_bf16 v[10:13], v[198:201], v[222:225], v[182:185]
	v_mfma_f32_16x16x32_bf16 v[30:33], v[202:205], v[226:229], v[10:13]
	v_mfma_f32_16x16x32_bf16 v[10:13], v[206:209], v[222:225], v[186:189]
	v_mfma_f32_16x16x32_bf16 v[26:29], v[210:213], v[226:229], v[10:13]
	v_mfma_f32_16x16x32_bf16 v[10:13], v[198:201], v[230:233], v[190:193]
	v_mfma_f32_16x16x32_bf16 v[14:17], v[202:205], v[234:237], v[10:13]
	v_mfma_f32_16x16x32_bf16 v[10:13], v[206:209], v[230:233], v[194:197]
	v_mfma_f32_16x16x32_bf16 v[10:13], v[210:213], v[234:237], v[10:13]
	s_barrier
	s_add_u32 s74, s74, 0x80180
	s_addc_u32 s75, s75, 0
	s_add_u32 s57, s72, 0x200
	s_addc_u32 s72, s73, 0
	s_mov_b32 s73, 0

; #define PG8_STAGE(bufoff, gbase, voff) do { if constexpr (!NOSTAGE) _Pragma("unroll") for (int _i = 0; _i < 2; ++_i) \
;         __builtin_amdgcn_global_load_lds((const unsigned*)((const char*)(gbase) + (size_t)_i * pstep##voff + v##voff), (PG8_LAS unsigned*)(lds + (bufoff) + ldsw + _i * 8192), 16, 0, 0); } while (0)
; #define PG8_BAR __builtin_amdgcn_s_barrier()
;     __host__ __device__ bool next(int i, Unit& u) const {
;         const long L = (long)i * G + c; if (L >= nwg) return false;
;         int wgid = (int)L; { const int q = nwg / NXCD, r = nwg % NXCD, xcd = wgid % NXCD, off = wgid / NXCD; wgid = (xcd < r ? xcd * (q + 1) : r * (q + 1) + (xcd - r) * q) + off; }
;         const int nig = WGM * nN, gid = wgid / nig, fm = gid * WGM, gsz = (nM - fm) < WGM ? (nM - fm) : WGM;
;         u.pm = fm + ((wgid % nig) % gsz); u.pn = (wgid % nig) / gsz; return true;
; template <class Epi, class Sched, bool ALIGN_EPI = true, bool SP2 = true, bool FULLLINE = false, bool NOSTAGE = false, bool FP8 = false>
; __device__ __forceinline__ void gemm_phase(PG8_LAS unsigned char* lds, const Gemm g, const Sched& S, const Epi& E) {
;     ...
;     const char* cA = PG8_ABASE(cur); const char* cB = PG8_BBASE(cur);
;     S.a_ready(cur);
;     if constexpr (SP2) {
;     PG8_STAGE(PG8_SB(0, 0), cB, offB); PG8_STAGE(PG8_SB(0, 1), cB + hstepB, offB); PG8_STAGE(PG8_SA(0, 0), cA, offA); PG8_STAGE(PG8_SA(0, 1), cA + hstepA, offA);
;     PG8_STAGE(PG8_SB(1, 0), cB + kstep, offB); PG8_STAGE(PG8_SA(1, 0), cA + kstep, offA); PG8_STAGE(PG8_SB(1, 1), cB + hstepB + kstep, offB);
;     if (wr == 1) PG8_BAR;
.LBB0_2850:
	s_cmp_lt_i32 s56, 30
	s_cselect_b64 s[0:1], -1, 0
	s_cmp_gt_i32 s57, 29
	s_cselect_b64 s[6:7], -1, 0
	s_and_b64 s[0:1], s[0:1], s[6:7]
	s_andn2_b64 vcc, exec, s[0:1]
	s_cbranch_vccnz .LBB0_2941
	v_mov_b32_e32 v1, v0
	s_cmpk_gt_i32 s2, 0xaff
	v_readfirstlane_b32 s9, v0
	s_cbranch_scc1 .LBB0_2869
	s_add_u32 s3, s48, 0x11b00000
	s_addc_u32 s42, s49, 0
	s_ashr_i32 s52, s2, 31
	s_lshr_b32 s0, s52, 29
	s_add_i32 s0, s2, s0
	s_waitcnt lgkmcnt(0)
	s_lshr_b32 s12, s9, 6
	s_ashr_i32 s1, s0, 3
	s_and_b32 s0, s0, -8
	s_lshr_b32 s13, s9, 8
	s_lshl_b32 s43, s12, 10
	s_sub_i32 s0, s2, s0
	s_cmp_lt_i32 s0, 0
	s_movk_i32 s6, 0x161
	s_cselect_b32 s6, s6, 0x160
	s_mul_i32 s0, s0, s6
	s_add_i32 s0, s0, s1
	s_mul_hi_i32 s1, s0, 0x2e8ba2e9
	s_lshr_b32 s6, s1, 31
	s_ashr_i32 s1, s1, 6
	s_add_i32 s1, s1, s6
	s_lshl_b32 s6, s1, 3
	s_mulk_i32 s1, 0x160
	s_sub_i32 s0, s0, s1
	s_sext_i32_i16 s1, s0
	s_bfe_u32 s1, s1, 0x3001c
	s_add_i32 s1, s0, s1
	s_sext_i32_i16 s7, s1
	s_and_b32 s1, s1, 0xfff8
	v_lshrrev_b32_e32 v1, 5, v0
	v_bfe_u32 v2, v0, 2, 2
	v_lshrrev_b32_e32 v4, 3, v0
	v_lshrrev_b32_e32 v3, 1, v0
	s_sub_i32 s0, s0, s1
	v_and_or_b32 v1, v1, 4, v2
	v_and_b32_e32 v2, 32, v4
	v_and_b32_e32 v3, 24, v3
	s_sext_i32_i16 s0, s0
	v_or3_b32 v3, v1, v2, v3
	v_lshlrev_b32_e32 v1, 4, v0
	v_and_b32_e32 v2, 32, v0
	s_lshr_b32 s8, s7, 3
	s_cmpk_lg_i32 s86, 0x100
	s_cbranch_scc1 .Lrot_skip_58177
	s_and_b32 s100, s2, 7
	s_mul_i32 s100, s100, 5
	s_add_i32 s8, s8, s100
	s_cmp_ge_i32 s8, 44
	s_cselect_b32 s100, 44, 0
	s_sub_i32 s8, s8, s100
.Lrot_skip_58177:
	s_add_i32 s66, s6, s0
	v_bitop3_b32 v1, v1, v2, 48 bitop3:0x6c
	v_and_b32_e32 v2, 64, v0
	s_ashr_i32 s67, s66, 31
	s_bfe_i64 s[6:7], s[8:9], 0x100000
	v_or_b32_e32 v5, v1, v2
	s_lshl_b64 s[0:1], s[66:67], 20
	s_lshl_b64 s[6:7], s[6:7], 20
	v_lshl_or_b32 v130, v3, 12, v5
	v_bfe_u32 v3, v0, 2, 4
	s_add_u32 s68, s3, s6
	v_and_or_b32 v4, v4, 48, v3
	s_addc_u32 s69, s42, s7
	v_mov_b32_e32 v131, 0
	s_add_i32 s53, s43, 0
	v_lshl_or_b32 v132, v4, 12, v5
	v_lshl_add_u64 v[4:5], s[68:69], 0, v[130:131]
	s_add_i32 m0, s53, 0x10000
	s_mov_b64 s[6:7], 0x40000
	global_load_lds_dwordx4 v130, s[68:69]
	v_lshl_add_u64 v[6:7], v[4:5], 0, s[6:7]
	s_add_i32 m0, s53, 0x12000
	s_mov_b64 s[10:11], 0x80000
	global_load_lds_dwordx4 v[6:7], off
	v_lshl_add_u64 v[6:7], v[4:5], 0, s[10:11]
	s_add_i32 m0, s53, 0x14000
	s_mov_b64 s[14:15], 0xc0000
	global_load_lds_dwordx4 v[6:7], off
	s_add_i32 m0, s53, 0x16000
	s_add_u32 s70, s58, s0
	v_lshl_add_u64 v[6:7], v[4:5], 0, s[14:15]
	s_addc_u32 s71, s59, s1
	v_mov_b32_e32 v133, v131
	global_load_lds_dwordx4 v[6:7], off
	v_lshl_add_u64 v[6:7], s[70:71], 0, v[132:133]
	s_mov_b32 m0, s53
	s_add_i32 s54, s53, 0x2000
	global_load_lds_dwordx4 v132, s[70:71]
	v_lshl_add_u64 v[8:9], v[6:7], 0, s[6:7]
	s_mov_b32 m0, s54
	s_add_i32 s55, s53, 0x4000
	global_load_lds_dwordx4 v[8:9], off
	v_lshl_add_u64 v[8:9], v[6:7], 0, s[10:11]
	s_mov_b32 m0, s55
	s_add_i32 s67, s53, 0x6000
	global_load_lds_dwordx4 v[8:9], off
	v_lshl_add_u64 v[8:9], v[6:7], 0, s[14:15]
	s_mov_b32 m0, s67
	s_mov_b64 s[0:1], 0x80
	global_load_lds_dwordx4 v[8:9], off
	v_lshl_add_u64 v[8:9], v[4:5], 0, s[0:1]
	s_add_i32 m0, s53, 0x18000
	s_mov_b64 s[6:7], 0x40080
	global_load_lds_dwordx4 v[8:9], off
	v_lshl_add_u64 v[8:9], v[4:5], 0, s[6:7]
	s_add_i32 m0, s53, 0x1a000
	s_add_i32 s72, s53, 0x8000
	global_load_lds_dwordx4 v[8:9], off
	v_lshl_add_u64 v[8:9], v[6:7], 0, s[0:1]
	s_mov_b32 m0, s72
	s_add_i32 s73, s53, 0xa000
	global_load_lds_dwordx4 v[8:9], off
	v_lshl_add_u64 v[6:7], v[6:7], 0, s[6:7]
	s_mov_b32 m0, s73
	s_mov_b64 s[0:1], 0x80080
	global_load_lds_dwordx4 v[6:7], off
	v_lshl_add_u64 v[6:7], v[4:5], 0, s[0:1]
	s_add_i32 m0, s53, 0x1c000
	s_mov_b64 s[0:1], 0xc0080
	global_load_lds_dwordx4 v[6:7], off
	v_lshl_add_u64 v[4:5], v[4:5], 0, s[0:1]
	s_add_i32 m0, s53, 0x1e000
	s_cmp_eq_u32 s13, 1
	global_load_lds_dwordx4 v[4:5], off
	s_cselect_b64 s[10:11], -1, 0
	s_cmp_lg_u32 s13, 1
	s_cbranch_scc1 .LBB0_2854
	s_barrier

;     __host__ __device__ bool next(int i, Unit& u) const {
;         const long L = (long)i * G + c; if (L >= nwg) return false;
;         int wgid = (int)L; { const int q = nwg / NXCD, r = nwg % NXCD, xcd = wgid % NXCD, off = wgid / NXCD; wgid = (xcd < r ? xcd * (q + 1) : r * (q + 1) + (xcd - r) * q) + off; }
;         const int nig = WGM * nN, gid = wgid / nig, fm = gid * WGM, gsz = (nM - fm) < WGM ? (nM - fm) : WGM;
;         u.pm = fm + ((wgid % nig) % gsz); u.pn = (wgid % nig) / gsz; return true;
; template <class Epi, class Sched, bool ALIGN_EPI = true, bool SP2 = true, bool FULLLINE = false, bool NOSTAGE = false, bool FP8 = false>
; __device__ __forceinline__ void gemm_phase(PG8_LAS unsigned char* lds, const Gemm g, const Sched& S, const Epi& E) {
;     ...
;         const bool has_next = S.next(ui + 1, nxt);
;         const char* nA = has_next ? PG8_ABASE(nxt) : cA; const char* nB = has_next ? PG8_BBASE(nxt) : cB;
.LBB0_2859:
	s_add_i32 s77, s77, 1
	s_mul_i32 s0, s77, s76
	s_mul_hi_u32 s1, s77, s86
	s_add_i32 s1, s1, s0
	s_mul_i32 s0, s77, s86
	s_add_u32 s46, s0, s2
	s_addc_u32 s47, s1, s52
	v_cmp_gt_i64_e32 vcc, s[46:47], v[138:139]
	v_cmp_lt_i64_e64 s[8:9], s[46:47], v[136:137]
	s_cbranch_vccnz .LBB0_2861
	s_ashr_i32 s0, s46, 31
	s_lshr_b32 s0, s0, 29
	s_add_i32 s0, s46, s0
	s_ashr_i32 s1, s0, 3
	s_and_b32 s0, s0, -8
	s_sub_i32 s0, s46, s0
	s_cmp_lt_i32 s0, 0
	s_movk_i32 s33, 0x161
	s_cselect_b32 s33, s33, 0x160
	s_mul_i32 s0, s0, s33
	s_add_i32 s0, s0, s1
	s_mul_hi_i32 s1, s0, 0x2e8ba2e9
	s_lshr_b32 s33, s1, 31
	s_ashr_i32 s1, s1, 6
	s_add_i32 s1, s1, s33
	s_lshl_b32 s33, s1, 3
	s_sub_i32 s40, 64, s33
	s_min_i32 s41, s40, 8
	s_abs_i32 s40, s41
	v_cvt_f32_u32_e32 v2, s40
	s_sub_i32 s45, 0, s40
	s_mulk_i32 s1, 0x160
	s_sub_i32 s0, s0, s1
	v_rcp_iflag_f32_e32 v2, v2
	s_abs_i32 s1, s0
	s_xor_b32 s44, s0, s41
	s_ashr_i32 s44, s44, 31
	v_mul_f32_e32 v2, 0x4f7ffffe, v2
	v_cvt_u32_f32_e32 v2, v2
	s_nop 0
	v_readfirstlane_b32 s46, v2
	s_mul_i32 s45, s45, s46
	s_mul_hi_u32 s45, s46, s45
	s_add_i32 s46, s46, s45
	s_mul_hi_u32 s45, s1, s46
	s_mul_i32 s46, s45, s40
	s_sub_i32 s1, s1, s46
	s_add_i32 s47, s45, 1
	s_sub_i32 s46, s1, s40
	s_cmp_ge_u32 s1, s40
	s_cselect_b32 s45, s47, s45
	s_cselect_b32 s1, s46, s1
	s_add_i32 s46, s45, 1
	s_cmp_ge_u32 s1, s40
	s_cselect_b32 s1, s46, s45
	s_xor_b32 s1, s1, s44
	s_sub_i32 s40, s1, s44
	s_mul_i32 s1, s40, s41
	s_sub_i32 s0, s0, s1
	s_add_i32 s44, s33, s0
	s_cmpk_lg_i32 s86, 0x100
	s_cbranch_scc1 .Lrot_skip_58396
	s_and_b32 s100, s2, 7
	s_mul_i32 s100, s100, 5
	s_add_i32 s40, s40, s100
	s_cmp_ge_i32 s40, 44
	s_cselect_b32 s100, 44, 0
	s_sub_i32 s40, s40, s100
.Lrot_skip_58396:
.LBB0_2861:
	s_ashr_i32 s45, s44, 31
	s_lshl_b64 s[0:1], s[44:45], 20
	s_add_u32 s46, s58, s0
	ds_read_b128 v[2:5], v1
	ds_read_b128 v[6:9], v1 offset:1024
	ds_read_b128 v[10:13], v1 offset:2048
	ds_read_b128 v[14:17], v1 offset:3072
	ds_read_b128 v[18:21], v142
	ds_read_b128 v[22:25], v142 offset:1024
	ds_read_b128 v[26:29], v142 offset:2048
	ds_read_b128 v[30:33], v142 offset:3072
	s_addc_u32 s47, s59, s1
	s_ashr_i32 s41, s40, 31
	s_lshl_b64 s[0:1], s[40:41], 20
	s_add_u32 s62, s3, s0
	s_addc_u32 s63, s42, s1
	s_and_b64 s[0:1], s[8:9], exec
	s_cselect_b32 s41, s47, s71
	s_cselect_b32 s45, s46, s70
	s_cselect_b32 s87, s63, s69
	s_cselect_b32 s88, s62, s68
	v_lshl_add_u64 v[140:141], s[70:71], 0, v[132:133]
	s_mov_b32 m0, s79
	v_lshl_add_u64 v[66:67], v[140:141], 0, s[12:13]
	ds_read_b128 v[34:37], v143
	ds_read_b128 v[38:41], v143 offset:1024
	ds_read_b128 v[42:45], v143 offset:2048
	ds_read_b128 v[46:49], v143 offset:3072
	ds_read_b128 v[50:53], v143 offset:4096
	ds_read_b128 v[54:57], v143 offset:5120
	ds_read_b128 v[58:61], v143 offset:6144
	ds_read_b128 v[62:65], v143 offset:7168
	global_load_lds_dwordx4 v[66:67], off
	v_lshl_add_u64 v[66:67], v[140:141], 0, s[14:15]
	s_mov_b32 m0, s80
	s_nop 0
	global_load_lds_dwordx4 v[66:67], off
	s_waitcnt vmcnt(16)
	s_waitcnt lgkmcnt(0)
	s_barrier
	s_waitcnt lgkmcnt(0)
	v_mfma_f32_16x16x32_bf16 v[86:89], v[10:13], v[50:53], 0
	v_mfma_f32_16x16x32_bf16 v[90:93], v[14:17], v[54:57], v[86:89]
	v_mfma_f32_16x16x32_bf16 v[86:89], v[2:5], v[58:61], 0
	v_mfma_f32_16x16x32_bf16 v[66:69], v[2:5], v[34:37], 0
	v_mfma_f32_16x16x32_bf16 v[70:73], v[10:13], v[34:37], 0
	v_mfma_f32_16x16x32_bf16 v[74:77], v[2:5], v[42:45], 0
	v_mfma_f32_16x16x32_bf16 v[78:81], v[10:13], v[42:45], 0
	v_mfma_f32_16x16x32_bf16 v[82:85], v[2:5], v[50:53], 0
	v_mfma_f32_16x16x32_bf16 v[94:97], v[6:9], v[62:65], v[86:89]
	v_mfma_f32_16x16x32_bf16 v[86:89], v[10:13], v[58:61], 0
	v_mfma_f32_16x16x32_bf16 v[66:69], v[6:9], v[38:41], v[66:69]
	v_mfma_f32_16x16x32_bf16 v[70:73], v[14:17], v[38:41], v[70:73]
	v_mfma_f32_16x16x32_bf16 v[74:77], v[6:9], v[46:49], v[74:77]
	v_mfma_f32_16x16x32_bf16 v[78:81], v[14:17], v[46:49], v[78:81]
	v_mfma_f32_16x16x32_bf16 v[82:85], v[6:9], v[54:57], v[82:85]
	v_mfma_f32_16x16x32_bf16 v[106:109], v[14:17], v[62:65], v[86:89]
	v_mfma_f32_16x16x32_bf16 v[86:89], v[18:21], v[34:37], 0
	v_mfma_f32_16x16x32_bf16 v[34:37], v[26:29], v[34:37], 0
	v_mfma_f32_16x16x32_bf16 v[110:113], v[22:25], v[38:41], v[86:89]
	v_mfma_f32_16x16x32_bf16 v[34:37], v[30:33], v[38:41], v[34:37]
	v_mfma_f32_16x16x32_bf16 v[38:41], v[18:21], v[42:45], 0
	v_mfma_f32_16x16x32_bf16 v[42:45], v[26:29], v[42:45], 0
	v_mfma_f32_16x16x32_bf16 v[38:41], v[22:25], v[46:49], v[38:41]
	v_mfma_f32_16x16x32_bf16 v[42:45], v[30:33], v[46:49], v[42:45]
	v_mfma_f32_16x16x32_bf16 v[46:49], v[18:21], v[50:53], 0
	v_mfma_f32_16x16x32_bf16 v[50:53], v[26:29], v[50:53], 0
	v_mfma_f32_16x16x32_bf16 v[46:49], v[22:25], v[54:57], v[46:49]
	v_mfma_f32_16x16x32_bf16 v[50:53], v[30:33], v[54:57], v[50:53]
	v_mfma_f32_16x16x32_bf16 v[54:57], v[18:21], v[58:61], 0
	v_mfma_f32_16x16x32_bf16 v[58:61], v[26:29], v[58:61], 0
	v_mfma_f32_16x16x32_bf16 v[54:57], v[22:25], v[62:65], v[54:57]
	v_mfma_f32_16x16x32_bf16 v[58:61], v[30:33], v[62:65], v[58:61]
	s_barrier
	v_lshl_add_u64 v[238:239], s[68:69], 0, v[130:131]
	s_mov_b32 m0, s81
	v_lshl_add_u64 v[146:147], v[238:239], 0, s[16:17]
	s_add_i32 s89, s81, 0x2000
	ds_read_b128 v[62:65], v143 offset:16384
	ds_read_b128 v[86:89], v143 offset:17408
	ds_read_b128 v[98:101], v143 offset:18432
	ds_read_b128 v[102:105], v143 offset:19456
	ds_read_b128 v[114:117], v143 offset:20480
	ds_read_b128 v[118:121], v143 offset:21504
	ds_read_b128 v[122:125], v143 offset:22528
	ds_read_b128 v[126:129], v143 offset:23552
	global_load_lds_dwordx4 v[146:147], off
	v_lshl_add_u64 v[146:147], v[238:239], 0, s[18:19]
	s_mov_b32 m0, s89
	s_add_i32 s90, s78, s43
	global_load_lds_dwordx4 v[146:147], off
	v_lshl_add_u64 v[146:147], v[238:239], 0, s[20:21]
	s_mov_b32 m0, s90
	s_add_i32 s91, s90, 0x2000
	global_load_lds_dwordx4 v[146:147], off
	v_lshl_add_u64 v[146:147], v[238:239], 0, s[22:23]
	s_mov_b32 m0, s91
	s_nop 0
	global_load_lds_dwordx4 v[146:147], off
	v_lshl_add_u64 v[146:147], v[140:141], 0, s[16:17]
	s_mov_b32 m0, s53
	s_nop 0
	global_load_lds_dwordx4 v[146:147], off
	v_lshl_add_u64 v[146:147], v[140:141], 0, s[18:19]
	s_mov_b32 m0, s54
	s_nop 0
	global_load_lds_dwordx4 v[146:147], off
	s_waitcnt vmcnt(16)
	s_waitcnt lgkmcnt(0)
	s_barrier
	s_waitcnt lgkmcnt(0)
	v_mfma_f32_16x16x32_bf16 v[146:149], v[2:5], v[62:65], 0
	v_mfma_f32_16x16x32_bf16 v[154:157], v[2:5], v[98:101], 0
	v_mfma_f32_16x16x32_bf16 v[162:165], v[2:5], v[114:117], 0
	v_mfma_f32_16x16x32_bf16 v[2:5], v[2:5], v[122:125], 0
	v_mfma_f32_16x16x32_bf16 v[146:149], v[6:9], v[86:89], v[146:149]
	v_mfma_f32_16x16x32_bf16 v[154:157], v[6:9], v[102:105], v[154:157]
	v_mfma_f32_16x16x32_bf16 v[162:165], v[6:9], v[118:121], v[162:165]
	v_mfma_f32_16x16x32_bf16 v[2:5], v[6:9], v[126:129], v[2:5]
	v_mfma_f32_16x16x32_bf16 v[6:9], v[10:13], v[122:125], 0
	v_mfma_f32_16x16x32_bf16 v[150:153], v[10:13], v[62:65], 0
	v_mfma_f32_16x16x32_bf16 v[158:161], v[10:13], v[98:101], 0
	v_mfma_f32_16x16x32_bf16 v[166:169], v[10:13], v[114:117], 0
	v_mfma_f32_16x16x32_bf16 v[10:13], v[14:17], v[126:129], v[6:9]
	v_mfma_f32_16x16x32_bf16 v[150:153], v[14:17], v[86:89], v[150:153]
	v_mfma_f32_16x16x32_bf16 v[158:161], v[14:17], v[102:105], v[158:161]
	v_mfma_f32_16x16x32_bf16 v[166:169], v[14:17], v[118:121], v[166:169]
	v_mfma_f32_16x16x32_bf16 v[6:9], v[18:21], v[62:65], 0
	v_mfma_f32_16x16x32_bf16 v[14:17], v[22:25], v[86:89], v[6:9]
	v_mfma_f32_16x16x32_bf16 v[6:9], v[26:29], v[62:65], 0
	v_mfma_f32_16x16x32_bf16 v[170:173], v[30:33], v[86:89], v[6:9]
	v_mfma_f32_16x16x32_bf16 v[6:9], v[18:21], v[98:101], 0
	v_mfma_f32_16x16x32_bf16 v[174:177], v[22:25], v[102:105], v[6:9]
	v_mfma_f32_16x16x32_bf16 v[6:9], v[26:29], v[98:101], 0
	v_mfma_f32_16x16x32_bf16 v[178:181], v[30:33], v[102:105], v[6:9]
	v_mfma_f32_16x16x32_bf16 v[6:9], v[18:21], v[114:117], 0
	v_mfma_f32_16x16x32_bf16 v[182:185], v[22:25], v[118:121], v[6:9]
	v_mfma_f32_16x16x32_bf16 v[6:9], v[26:29], v[114:117], 0
	v_mfma_f32_16x16x32_bf16 v[186:189], v[30:33], v[118:121], v[6:9]
	v_mfma_f32_16x16x32_bf16 v[6:9], v[18:21], v[122:125], 0
	v_mfma_f32_16x16x32_bf16 v[190:193], v[22:25], v[126:129], v[6:9]
	v_mfma_f32_16x16x32_bf16 v[6:9], v[26:29], v[122:125], 0
	v_mfma_f32_16x16x32_bf16 v[194:197], v[30:33], v[126:129], v[6:9]
	s_barrier
	s_nop 5
	ds_read_b128 v[6:9], v144
	ds_read_b128 v[26:29], v144 offset:1024
	ds_read_b128 v[30:33], v144 offset:2048
	ds_read_b128 v[62:65], v144 offset:3072
	ds_read_b128 v[198:201], v145
	ds_read_b128 v[202:205], v145 offset:1024
	ds_read_b128 v[206:209], v145 offset:2048
	ds_read_b128 v[210:213], v145 offset:3072
	s_mov_b32 m0, s55
	v_lshl_add_u64 v[86:87], v[140:141], 0, s[20:21]
	ds_read_b128 v[18:21], v143 offset:32768
	ds_read_b128 v[22:25], v143 offset:33792
	ds_read_b128 v[214:217], v143 offset:34816
	ds_read_b128 v[218:221], v143 offset:35840
	ds_read_b128 v[222:225], v143 offset:36864
	ds_read_b128 v[226:229], v143 offset:37888
	ds_read_b128 v[230:233], v143 offset:38912
	ds_read_b128 v[234:237], v143 offset:39936
	global_load_lds_dwordx4 v[86:87], off
	v_lshl_add_u64 v[86:87], v[140:141], 0, s[22:23]
	s_mov_b32 m0, s67
	s_nop 0
	global_load_lds_dwordx4 v[86:87], off
	s_waitcnt vmcnt(8)
	s_waitcnt lgkmcnt(0)
	s_barrier
	s_waitcnt lgkmcnt(0)
	v_mfma_f32_16x16x32_bf16 v[66:69], v[6:9], v[18:21], v[66:69]
	v_mfma_f32_16x16x32_bf16 v[118:121], v[26:29], v[22:25], v[66:69]
	v_mfma_f32_16x16x32_bf16 v[66:69], v[30:33], v[18:21], v[70:73]
	v_mfma_f32_16x16x32_bf16 v[114:117], v[62:65], v[22:25], v[66:69]
	v_mfma_f32_16x16x32_bf16 v[66:69], v[6:9], v[214:217], v[74:77]
	v_mfma_f32_16x16x32_bf16 v[102:105], v[26:29], v[218:221], v[66:69]
	v_mfma_f32_16x16x32_bf16 v[66:69], v[30:33], v[214:217], v[78:81]
	v_mfma_f32_16x16x32_bf16 v[98:101], v[62:65], v[218:221], v[66:69]
	v_mfma_f32_16x16x32_bf16 v[66:69], v[6:9], v[222:225], v[82:85]
	v_mfma_f32_16x16x32_bf16 v[86:89], v[26:29], v[226:229], v[66:69]
	v_mfma_f32_16x16x32_bf16 v[66:69], v[30:33], v[222:225], v[90:93]
	v_mfma_f32_16x16x32_bf16 v[82:85], v[62:65], v[226:229], v[66:69]
	v_mfma_f32_16x16x32_bf16 v[66:69], v[6:9], v[230:233], v[94:97]
	v_mfma_f32_16x16x32_bf16 v[70:73], v[26:29], v[234:237], v[66:69]
	v_mfma_f32_16x16x32_bf16 v[66:69], v[30:33], v[230:233], v[106:109]
	v_mfma_f32_16x16x32_bf16 v[66:69], v[62:65], v[234:237], v[66:69]
	v_mfma_f32_16x16x32_bf16 v[74:77], v[198:201], v[18:21], v[110:113]
	v_mfma_f32_16x16x32_bf16 v[18:21], v[206:209], v[18:21], v[34:37]
	v_mfma_f32_16x16x32_bf16 v[122:125], v[210:213], v[22:25], v[18:21]
	v_mfma_f32_16x16x32_bf16 v[18:21], v[198:201], v[214:217], v[38:41]
	v_mfma_f32_16x16x32_bf16 v[110:113], v[202:205], v[218:221], v[18:21]
	v_mfma_f32_16x16x32_bf16 v[18:21], v[206:209], v[214:217], v[42:45]
	v_mfma_f32_16x16x32_bf16 v[106:109], v[210:213], v[218:221], v[18:21]
	v_mfma_f32_16x16x32_bf16 v[18:21], v[198:201], v[222:225], v[46:49]
	v_mfma_f32_16x16x32_bf16 v[94:97], v[202:205], v[226:229], v[18:21]
	v_mfma_f32_16x16x32_bf16 v[18:21], v[206:209], v[222:225], v[50:53]
	v_mfma_f32_16x16x32_bf16 v[90:93], v[210:213], v[226:229], v[18:21]
	v_mfma_f32_16x16x32_bf16 v[18:21], v[198:201], v[230:233], v[54:57]
	v_mfma_f32_16x16x32_bf16 v[78:81], v[202:205], v[234:237], v[18:21]
	v_mfma_f32_16x16x32_bf16 v[18:21], v[206:209], v[230:233], v[58:61]
	v_mfma_f32_16x16x32_bf16 v[126:129], v[202:205], v[22:25], v[74:77]
	v_mfma_f32_16x16x32_bf16 v[74:77], v[210:213], v[234:237], v[18:21]
	s_barrier
	s_add_i32 s50, s82, s43
	s_nop 3
	v_lshl_add_u64 v[18:19], v[238:239], 0, s[24:25]
	s_mov_b32 m0, s50
	s_add_i32 s51, s50, 0x2000
	ds_read_b128 v[42:45], v143 offset:49152
	ds_read_b128 v[46:49], v143 offset:50176
	ds_read_b128 v[214:217], v143 offset:51200
	ds_read_b128 v[218:221], v143 offset:52224
	ds_read_b128 v[222:225], v143 offset:53248
	ds_read_b128 v[226:229], v143 offset:54272
	ds_read_b128 v[230:233], v143 offset:55296
	ds_read_b128 v[234:237], v143 offset:56320
	global_load_lds_dwordx4 v[18:19], off
	v_lshl_add_u64 v[18:19], v[238:239], 0, s[26:27]
	s_mov_b32 m0, s51
	s_mov_b64 s[0:1], 0x80180
	s_add_i32 s33, s83, s43
	global_load_lds_dwordx4 v[18:19], off
	v_lshl_add_u64 v[18:19], v[238:239], 0, s[0:1]
	s_mov_b32 m0, s33
	s_mov_b64 s[0:1], 0xc0180
	s_add_i32 s56, s33, 0x2000
	global_load_lds_dwordx4 v[18:19], off
	v_lshl_add_u64 v[18:19], v[238:239], 0, s[0:1]
	s_mov_b32 m0, s56
	s_nop 0
	global_load_lds_dwordx4 v[18:19], off
	v_lshl_add_u64 v[18:19], v[140:141], 0, s[24:25]
	s_mov_b32 m0, s72
	s_nop 0
	global_load_lds_dwordx4 v[18:19], off
	v_lshl_add_u64 v[18:19], v[140:141], 0, s[26:27]
	s_mov_b32 m0, s73
	s_nop 0
	global_load_lds_dwordx4 v[18:19], off
	s_waitcnt vmcnt(8)
	s_waitcnt lgkmcnt(0)
	s_barrier
	s_waitcnt lgkmcnt(0)
	v_mfma_f32_16x16x32_bf16 v[18:21], v[6:9], v[42:45], v[146:149]
	v_mfma_f32_16x16x32_bf16 v[54:57], v[26:29], v[46:49], v[18:21]
	v_mfma_f32_16x16x32_bf16 v[18:21], v[30:33], v[42:45], v[150:153]
	v_mfma_f32_16x16x32_bf16 v[50:53], v[62:65], v[46:49], v[18:21]
	v_mfma_f32_16x16x32_bf16 v[18:21], v[6:9], v[214:217], v[154:157]
	v_mfma_f32_16x16x32_bf16 v[38:41], v[26:29], v[218:221], v[18:21]
	v_mfma_f32_16x16x32_bf16 v[18:21], v[30:33], v[214:217], v[158:161]
	v_mfma_f32_16x16x32_bf16 v[34:37], v[62:65], v[218:221], v[18:21]
	v_mfma_f32_16x16x32_bf16 v[18:21], v[6:9], v[222:225], v[162:165]
	v_mfma_f32_16x16x32_bf16 v[2:5], v[6:9], v[230:233], v[2:5]
	v_mfma_f32_16x16x32_bf16 v[22:25], v[26:29], v[226:229], v[18:21]
	v_mfma_f32_16x16x32_bf16 v[18:21], v[30:33], v[222:225], v[166:169]
	v_mfma_f32_16x16x32_bf16 v[6:9], v[26:29], v[234:237], v[2:5]
	v_mfma_f32_16x16x32_bf16 v[2:5], v[30:33], v[230:233], v[10:13]
	v_mfma_f32_16x16x32_bf16 v[18:21], v[62:65], v[226:229], v[18:21]
	v_mfma_f32_16x16x32_bf16 v[2:5], v[62:65], v[234:237], v[2:5]
	v_mfma_f32_16x16x32_bf16 v[10:13], v[198:201], v[42:45], v[14:17]
	v_mfma_f32_16x16x32_bf16 v[62:65], v[202:205], v[46:49], v[10:13]
	v_mfma_f32_16x16x32_bf16 v[10:13], v[206:209], v[42:45], v[170:173]
	v_mfma_f32_16x16x32_bf16 v[58:61], v[210:213], v[46:49], v[10:13]
	v_mfma_f32_16x16x32_bf16 v[10:13], v[198:201], v[214:217], v[174:177]
	v_mfma_f32_16x16x32_bf16 v[46:49], v[202:205], v[218:221], v[10:13]
	v_mfma_f32_16x16x32_bf16 v[10:13], v[206:209], v[214:217], v[178:181]
	v_mfma_f32_16x16x32_bf16 v[42:45], v[210:213], v[218:221], v[10:13]
	v_mfma_f32_16x16x32_bf16 v[10:13], v[198:201], v[222:225], v[182:185]
	v_mfma_f32_16x16x32_bf16 v[30:33], v[202:205], v[226:229], v[10:13]
	v_mfma_f32_16x16x32_bf16 v[10:13], v[206:209], v[222:225], v[186:189]
	v_mfma_f32_16x16x32_bf16 v[26:29], v[210:213], v[226:229], v[10:13]
	v_mfma_f32_16x16x32_bf16 v[10:13], v[198:201], v[230:233], v[190:193]
	v_mfma_f32_16x16x32_bf16 v[14:17], v[202:205], v[234:237], v[10:13]
	v_mfma_f32_16x16x32_bf16 v[10:13], v[206:209], v[230:233], v[194:197]
	v_mfma_f32_16x16x32_bf16 v[10:13], v[210:213], v[234:237], v[10:13]
	s_barrier
	s_add_u32 s70, s70, 0x80180
	s_addc_u32 s71, s71, 0
	s_add_u32 s57, s68, 0x200
	s_addc_u32 s68, s69, 0
	s_mov_b32 s69, 0
